# K-loops: s_setprio 1 raised before the segment barrier, s_setprio 0 dropped after the closing barrier, redundant lgkmcnt(0) removed (MFMA segment = barrier, 32 MFMA, barrier)
# baseline (speedup 1.0000x reference)
; #define PG8_STAGE(bufoff, gbase, voff) do { _Pragma("unroll") for (int _i = 0; _i < 2; ++_i) \
;         __builtin_amdgcn_global_load_lds((const unsigned*)((const char*)(gbase) + (voff)[_i]), (LAS unsigned*)(lds + (bufoff) + ldsw + _i * 8192), 16, 0, 0); } while (0)
; #define PG8_LDA(dst, b, h) do { _Pragma("unroll") for (int m = 0; m < 4; ++m) _Pragma("unroll") for (int k = 0; k < 2; ++k) dst[m][k] = *(const LAS bf16x8*)(lds + PG8_SA(b, h) + aoff + m * 2048 + k * 1024); } while (0)
; #define PG8_LDB(dst, b, h) do { _Pragma("unroll") for (int n = 0; n < 2; ++n) _Pragma("unroll") for (int k = 0; k < 2; ++k) dst[n][k] = *(const LAS bf16x8*)(lds + PG8_SB(b, h) + boff + n * 2048 + k * 1024); } while (0)
; #define PG8_MMA(ai, bj, At, Bt) do { __builtin_amdgcn_s_setprio(1); _Pragma("unroll") for (int m = 0; m < 4; ++m) _Pragma("unroll") for (int n = 0; n < 2; ++n) _Pragma("unroll") for (int k = 0; k < 2; ++k) \
;         acc[ai][bj][m][n] = MFMA16(Bt[n][k], At[m][k], acc[ai][bj][m][n]); __builtin_amdgcn_s_setprio(0); } while (0)
; #define PG8_WAIT_V(n) asm volatile("s_waitcnt vmcnt(" #n ")" ::: "memory")
; #define PG8_WAIT_L(n) asm volatile("s_waitcnt lgkmcnt(" #n ")" ::: "memory")
; #define PG8_BAR __builtin_amdgcn_s_barrier()
; #define PG8_SCHED __builtin_amdgcn_sched_barrier(0)
; template <class Epi>
; __device__ __forceinline__ void gemm_phase(LAS unsigned char* lds, const Gemm g, const StaticOrder& S, const Epi& E, int tid_) {
;     ...
;             const bool last = (t == nt - 2);
;             const char* a1 = cA + (size_t)(t + 1) * kstep;
;             const char* a2 = last ? nA : cA + (size_t)(t + 2) * kstep; const char* b2 = last ? nB : cB + (size_t)(t + 2) * kstep;
;             const char* a3 = a2 + kstep; const char* b3 = b2 + kstep;
;             PG8_LDB(B0, 0, 0); PG8_LDB(B1, 0, 1); PG8_SCHED; PG8_LDA(At, 0, 0); PG8_STAGE(PG8_SA(1, 1), a1 + hsA, voffA);
;             PG8_WAIT_V(8); PG8_WAIT_L(0); PG8_BAR; PG8_MMA(0, 0, At, B0); PG8_MMA(0, 1, At, B1); PG8_BAR; PG8_SCHED;
;             PG8_LDA(At, 0, 1); PG8_STAGE(PG8_SB(0, 0), b2, voffB); PG8_STAGE(PG8_SB(0, 1), b2 + hsB, voffB); PG8_STAGE(PG8_SA(0, 0), a2, voffA);
;             PG8_WAIT_V(8); PG8_WAIT_L(0); PG8_BAR; PG8_MMA(1, 0, At, B0); PG8_MMA(1, 1, At, B1); PG8_BAR; PG8_SCHED;
.LBB0_85:
	s_add_i32 s70, s40, 2
	s_add_u32 s41, s28, 0xfffc0080
	s_addc_u32 s56, s29, -1
	s_add_i32 s71, 0, 0x10000
	s_cmp_eq_u32 s64, s40
	s_cselect_b32 s57, s22, s56
	s_cselect_b32 s56, s23, s41
	s_cselect_b32 s41, s27, s69
	s_cselect_b32 s40, s51, s68
	s_add_i32 s74, 0, 0x14000
	v_add_u32_e32 v142, s71, v165
	v_add_u32_e32 v162, s74, v165
	ds_read_b128 v[130:133], v142
	ds_read_b128 v[134:137], v142 offset:1024
	ds_read_b128 v[138:141], v142 offset:2048
	ds_read_b128 v[142:145], v142 offset:3072
	ds_read_b128 v[158:161], v162
	ds_read_b128 v[174:177], v162 offset:1024
	ds_read_b128 v[178:181], v162 offset:2048
	ds_read_b128 v[198:201], v162 offset:3072
	v_lshl_add_u64 v[162:163], s[28:29], 0, v[154:155]
	s_add_i32 m0, s58, 0xc000
	ds_read_b128 v[202:205], v172
	ds_read_b128 v[206:209], v172 offset:1024
	ds_read_b128 v[216:219], v172 offset:2048
	ds_read_b128 v[220:223], v172 offset:3072
	ds_read_b128 v[224:227], v172 offset:4096
	ds_read_b128 v[228:231], v172 offset:5120
	ds_read_b128 v[232:235], v172 offset:6144
	ds_read_b128 v[236:239], v172 offset:7168
	global_load_lds_dwordx4 v[162:163], off
	v_lshl_add_u64 v[162:163], s[28:29], 0, v[156:157]
	s_add_i32 m0, s58, 0xe000
	s_nop 0
	global_load_lds_dwordx4 v[162:163], off
	s_waitcnt vmcnt(8)
	s_waitcnt lgkmcnt(0)
	s_setprio 1
	s_barrier
	v_mfma_f32_16x16x32_bf16 v[122:125], v[130:133], v[202:205], v[122:125]
	v_mfma_f32_16x16x32_bf16 v[118:121], v[138:141], v[202:205], v[118:121]
	v_mfma_f32_16x16x32_bf16 v[110:113], v[130:133], v[216:219], v[110:113]
	v_mfma_f32_16x16x32_bf16 v[102:105], v[138:141], v[216:219], v[102:105]
	v_mfma_f32_16x16x32_bf16 v[94:97], v[130:133], v[224:227], v[94:97]
	v_mfma_f32_16x16x32_bf16 v[86:89], v[138:141], v[224:227], v[86:89]
	v_mfma_f32_16x16x32_bf16 v[76:79], v[130:133], v[232:235], v[76:79]
	v_mfma_f32_16x16x32_bf16 v[68:71], v[138:141], v[232:235], v[68:71]
	v_mfma_f32_16x16x32_bf16 v[122:125], v[134:137], v[206:209], v[122:125]
	v_mfma_f32_16x16x32_bf16 v[118:121], v[142:145], v[206:209], v[118:121]
	v_mfma_f32_16x16x32_bf16 v[110:113], v[134:137], v[220:223], v[110:113]
	v_mfma_f32_16x16x32_bf16 v[102:105], v[142:145], v[220:223], v[102:105]
	v_mfma_f32_16x16x32_bf16 v[94:97], v[134:137], v[228:231], v[94:97]
	v_mfma_f32_16x16x32_bf16 v[86:89], v[142:145], v[228:231], v[86:89]
	v_mfma_f32_16x16x32_bf16 v[76:79], v[134:137], v[236:239], v[76:79]
	v_mfma_f32_16x16x32_bf16 v[68:71], v[142:145], v[236:239], v[68:71]
	v_mfma_f32_16x16x32_bf16 v[126:129], v[158:161], v[202:205], v[126:129]
	v_mfma_f32_16x16x32_bf16 v[114:117], v[178:181], v[202:205], v[114:117]
	v_mfma_f32_16x16x32_bf16 v[106:109], v[158:161], v[216:219], v[106:109]
	v_mfma_f32_16x16x32_bf16 v[98:101], v[178:181], v[216:219], v[98:101]
	v_mfma_f32_16x16x32_bf16 v[90:93], v[158:161], v[224:227], v[90:93]
	v_mfma_f32_16x16x32_bf16 v[82:85], v[178:181], v[224:227], v[82:85]
	v_mfma_f32_16x16x32_bf16 v[72:75], v[158:161], v[232:235], v[72:75]
	v_mfma_f32_16x16x32_bf16 v[64:67], v[178:181], v[232:235], v[64:67]
	v_mfma_f32_16x16x32_bf16 v[126:129], v[174:177], v[206:209], v[126:129]
	v_mfma_f32_16x16x32_bf16 v[114:117], v[198:201], v[206:209], v[114:117]
	v_mfma_f32_16x16x32_bf16 v[106:109], v[174:177], v[220:223], v[106:109]
	v_mfma_f32_16x16x32_bf16 v[98:101], v[198:201], v[220:223], v[98:101]
	v_mfma_f32_16x16x32_bf16 v[90:93], v[174:177], v[228:231], v[90:93]
	v_mfma_f32_16x16x32_bf16 v[82:85], v[198:201], v[228:231], v[82:85]
	v_mfma_f32_16x16x32_bf16 v[72:75], v[174:177], v[236:239], v[72:75]
	v_mfma_f32_16x16x32_bf16 v[64:67], v[198:201], v[236:239], v[64:67]
	s_barrier
	s_setprio 0
	s_add_i32 s71, s71, s31
	v_lshl_add_u64 v[162:163], s[40:41], 0, v[150:151]
	s_mov_b32 m0, s71
	ds_read_b128 v[202:205], v172 offset:16384
	ds_read_b128 v[206:209], v172 offset:17408
	ds_read_b128 v[216:219], v172 offset:18432
	ds_read_b128 v[220:223], v172 offset:19456
	ds_read_b128 v[224:227], v172 offset:20480
	ds_read_b128 v[228:231], v172 offset:21504
	ds_read_b128 v[232:235], v172 offset:22528
	ds_read_b128 v[236:239], v172 offset:23552
	global_load_lds_dwordx4 v[162:163], off
	s_add_i32 m0, s71, 0x2000
	s_add_u32 s72, s40, 0x40000
	v_lshl_add_u64 v[240:241], s[40:41], 0, v[146:147]
	s_addc_u32 s73, s41, 0
	s_add_i32 s71, s74, s31
	global_load_lds_dwordx4 v[240:241], off
	v_lshl_add_u64 v[242:243], s[72:73], 0, v[150:151]
	s_mov_b32 m0, s71
	v_lshl_add_u64 v[244:245], s[56:57], 0, v[148:149]
	global_load_lds_dwordx4 v[242:243], off
	v_lshl_add_u64 v[242:243], s[72:73], 0, v[146:147]
	s_add_i32 m0, s71, 0x2000
	s_nop 0
	global_load_lds_dwordx4 v[242:243], off
	v_lshl_add_u64 v[242:243], s[56:57], 0, v[152:153]
	s_mov_b32 m0, s58
	s_nop 0
	global_load_lds_dwordx4 v[242:243], off
	s_mov_b32 m0, s59
	s_nop 0
	global_load_lds_dwordx4 v[244:245], off
	s_waitcnt vmcnt(8)
	s_waitcnt lgkmcnt(0)
	s_setprio 1
	s_barrier
; #define PG8_STAGE(bufoff, gbase, voff) do { _Pragma("unroll") for (int _i = 0; _i < 2; ++_i) \
;         __builtin_amdgcn_global_load_lds((const unsigned*)((const char*)(gbase) + (voff)[_i]), (LAS unsigned*)(lds + (bufoff) + ldsw + _i * 8192), 16, 0, 0); } while (0)
; #define PG8_LDA(dst, b, h) do { _Pragma("unroll") for (int m = 0; m < 4; ++m) _Pragma("unroll") for (int k = 0; k < 2; ++k) dst[m][k] = *(const LAS bf16x8*)(lds + PG8_SA(b, h) + aoff + m * 2048 + k * 1024); } while (0)
; #define PG8_LDB(dst, b, h) do { _Pragma("unroll") for (int n = 0; n < 2; ++n) _Pragma("unroll") for (int k = 0; k < 2; ++k) dst[n][k] = *(const LAS bf16x8*)(lds + PG8_SB(b, h) + boff + n * 2048 + k * 1024); } while (0)
; #define PG8_MMA(ai, bj, At, Bt) do { __builtin_amdgcn_s_setprio(1); _Pragma("unroll") for (int m = 0; m < 4; ++m) _Pragma("unroll") for (int n = 0; n < 2; ++n) _Pragma("unroll") for (int k = 0; k < 2; ++k) \
;         acc[ai][bj][m][n] = MFMA16(Bt[n][k], At[m][k], acc[ai][bj][m][n]); __builtin_amdgcn_s_setprio(0); } while (0)
; #define PG8_WAIT_V(n) asm volatile("s_waitcnt vmcnt(" #n ")" ::: "memory")
; #define PG8_WAIT_L(n) asm volatile("s_waitcnt lgkmcnt(" #n ")" ::: "memory")
; #define PG8_BAR __builtin_amdgcn_s_barrier()
; #define PG8_SCHED __builtin_amdgcn_sched_barrier(0)
; template <class Epi>
; __device__ __forceinline__ void gemm_phase(LAS unsigned char* lds, const Gemm g, const StaticOrder& S, const Epi& E, int tid_) {
;     ...
;             PG8_WAIT_V(8); PG8_WAIT_L(0); PG8_BAR; PG8_MMA(1, 0, At, B0); PG8_MMA(1, 1, At, B1); PG8_BAR; PG8_SCHED;
;             PG8_LDB(B0, 1, 0); PG8_LDB(B1, 1, 1); PG8_SCHED; PG8_LDA(At, 1, 0); PG8_STAGE(PG8_SA(0, 1), a2 + hsA, voffA);
;             PG8_WAIT_V(8); PG8_WAIT_L(0); PG8_BAR; PG8_MMA(0, 0, At, B0); PG8_MMA(0, 1, At, B1); PG8_BAR; PG8_SCHED;
	v_mfma_f32_16x16x32_bf16 v[60:63], v[130:133], v[202:205], v[60:63]
	v_mfma_f32_16x16x32_bf16 v[52:55], v[138:141], v[202:205], v[52:55]
	v_mfma_f32_16x16x32_bf16 v[44:47], v[130:133], v[216:219], v[44:47]
	v_mfma_f32_16x16x32_bf16 v[36:39], v[138:141], v[216:219], v[36:39]
	v_mfma_f32_16x16x32_bf16 v[28:31], v[130:133], v[224:227], v[28:31]
	v_mfma_f32_16x16x32_bf16 v[20:23], v[138:141], v[224:227], v[20:23]
	v_mfma_f32_16x16x32_bf16 v[12:15], v[130:133], v[232:235], v[12:15]
	v_mfma_f32_16x16x32_bf16 v[4:7], v[138:141], v[232:235], v[4:7]
	v_mfma_f32_16x16x32_bf16 v[60:63], v[134:137], v[206:209], v[60:63]
	v_mfma_f32_16x16x32_bf16 v[52:55], v[142:145], v[206:209], v[52:55]
	v_mfma_f32_16x16x32_bf16 v[44:47], v[134:137], v[220:223], v[44:47]
	v_mfma_f32_16x16x32_bf16 v[36:39], v[142:145], v[220:223], v[36:39]
	v_mfma_f32_16x16x32_bf16 v[28:31], v[134:137], v[228:231], v[28:31]
	v_mfma_f32_16x16x32_bf16 v[20:23], v[142:145], v[228:231], v[20:23]
	v_mfma_f32_16x16x32_bf16 v[12:15], v[134:137], v[236:239], v[12:15]
	v_mfma_f32_16x16x32_bf16 v[4:7], v[142:145], v[236:239], v[4:7]
	v_mfma_f32_16x16x32_bf16 v[56:59], v[158:161], v[202:205], v[56:59]
	v_mfma_f32_16x16x32_bf16 v[48:51], v[178:181], v[202:205], v[48:51]
	v_mfma_f32_16x16x32_bf16 v[40:43], v[158:161], v[216:219], v[40:43]
	v_mfma_f32_16x16x32_bf16 v[32:35], v[178:181], v[216:219], v[32:35]
	v_mfma_f32_16x16x32_bf16 v[24:27], v[158:161], v[224:227], v[24:27]
	v_mfma_f32_16x16x32_bf16 v[16:19], v[178:181], v[224:227], v[16:19]
	v_mfma_f32_16x16x32_bf16 v[8:11], v[158:161], v[232:235], v[8:11]
	v_mfma_f32_16x16x32_bf16 v[0:3], v[178:181], v[232:235], v[0:3]
	v_mfma_f32_16x16x32_bf16 v[56:59], v[174:177], v[206:209], v[56:59]
	v_mfma_f32_16x16x32_bf16 v[48:51], v[198:201], v[206:209], v[48:51]
	v_mfma_f32_16x16x32_bf16 v[40:43], v[174:177], v[220:223], v[40:43]
	v_mfma_f32_16x16x32_bf16 v[32:35], v[198:201], v[220:223], v[32:35]
	v_mfma_f32_16x16x32_bf16 v[24:27], v[174:177], v[228:231], v[24:27]
	v_mfma_f32_16x16x32_bf16 v[16:19], v[198:201], v[228:231], v[16:19]
	v_mfma_f32_16x16x32_bf16 v[8:11], v[174:177], v[236:239], v[8:11]
	v_mfma_f32_16x16x32_bf16 v[0:3], v[198:201], v[236:239], v[0:3]
	s_barrier
	s_setprio 0
	s_add_i32 s71, 0, 0x18000
	s_add_i32 s72, 0, 0x1c000
	v_add_u32_e32 v142, s71, v165
	v_add_u32_e32 v173, s72, v165
	ds_read_b128 v[130:133], v142
	ds_read_b128 v[134:137], v142 offset:1024
	ds_read_b128 v[138:141], v142 offset:2048
	ds_read_b128 v[142:145], v142 offset:3072
	ds_read_b128 v[158:161], v173
	ds_read_b128 v[174:177], v173 offset:1024
	ds_read_b128 v[178:181], v173 offset:2048
	ds_read_b128 v[198:201], v173 offset:3072
	s_add_u32 s56, s56, 0x40000
	s_addc_u32 s57, s57, 0
	s_mov_b32 m0, s60
	v_lshl_add_u64 v[246:247], s[56:57], 0, v[152:153]
	ds_read_b128 v[202:205], v172 offset:32768
	ds_read_b128 v[206:209], v172 offset:33792
	ds_read_b128 v[216:219], v172 offset:34816
	ds_read_b128 v[220:223], v172 offset:35840
	ds_read_b128 v[224:227], v172 offset:36864
	ds_read_b128 v[228:231], v172 offset:37888
	ds_read_b128 v[232:235], v172 offset:38912
	ds_read_b128 v[236:239], v172 offset:39936
	global_load_lds_dwordx4 v[246:247], off
	v_lshl_add_u64 v[246:247], s[56:57], 0, v[148:149]
	s_mov_b32 m0, s61
	s_nop 0
	global_load_lds_dwordx4 v[246:247], off
	s_waitcnt vmcnt(8)
	s_waitcnt lgkmcnt(0)
	s_setprio 1
	s_barrier
	v_mfma_f32_16x16x32_bf16 v[122:125], v[130:133], v[202:205], v[122:125]
	v_mfma_f32_16x16x32_bf16 v[118:121], v[138:141], v[202:205], v[118:121]
	v_mfma_f32_16x16x32_bf16 v[110:113], v[130:133], v[216:219], v[110:113]
	v_mfma_f32_16x16x32_bf16 v[102:105], v[138:141], v[216:219], v[102:105]
	v_mfma_f32_16x16x32_bf16 v[94:97], v[130:133], v[224:227], v[94:97]
	v_mfma_f32_16x16x32_bf16 v[86:89], v[138:141], v[224:227], v[86:89]
	v_mfma_f32_16x16x32_bf16 v[76:79], v[130:133], v[232:235], v[76:79]
	v_mfma_f32_16x16x32_bf16 v[68:71], v[138:141], v[232:235], v[68:71]
	v_mfma_f32_16x16x32_bf16 v[122:125], v[134:137], v[206:209], v[122:125]
	v_mfma_f32_16x16x32_bf16 v[118:121], v[142:145], v[206:209], v[118:121]
	v_mfma_f32_16x16x32_bf16 v[110:113], v[134:137], v[220:223], v[110:113]
	v_mfma_f32_16x16x32_bf16 v[102:105], v[142:145], v[220:223], v[102:105]
	v_mfma_f32_16x16x32_bf16 v[94:97], v[134:137], v[228:231], v[94:97]
	v_mfma_f32_16x16x32_bf16 v[86:89], v[142:145], v[228:231], v[86:89]
	v_mfma_f32_16x16x32_bf16 v[76:79], v[134:137], v[236:239], v[76:79]
	v_mfma_f32_16x16x32_bf16 v[68:71], v[142:145], v[236:239], v[68:71]
	v_mfma_f32_16x16x32_bf16 v[126:129], v[158:161], v[202:205], v[126:129]
	v_mfma_f32_16x16x32_bf16 v[114:117], v[178:181], v[202:205], v[114:117]
	v_mfma_f32_16x16x32_bf16 v[106:109], v[158:161], v[216:219], v[106:109]
	v_mfma_f32_16x16x32_bf16 v[98:101], v[178:181], v[216:219], v[98:101]
	v_mfma_f32_16x16x32_bf16 v[90:93], v[158:161], v[224:227], v[90:93]
	v_mfma_f32_16x16x32_bf16 v[82:85], v[178:181], v[224:227], v[82:85]
	v_mfma_f32_16x16x32_bf16 v[72:75], v[158:161], v[232:235], v[72:75]
	v_mfma_f32_16x16x32_bf16 v[64:67], v[178:181], v[232:235], v[64:67]
	v_mfma_f32_16x16x32_bf16 v[126:129], v[174:177], v[206:209], v[126:129]
	v_mfma_f32_16x16x32_bf16 v[114:117], v[198:201], v[206:209], v[114:117]
	v_mfma_f32_16x16x32_bf16 v[106:109], v[174:177], v[220:223], v[106:109]
	v_mfma_f32_16x16x32_bf16 v[98:101], v[198:201], v[220:223], v[98:101]
	v_mfma_f32_16x16x32_bf16 v[90:93], v[174:177], v[228:231], v[90:93]
	v_mfma_f32_16x16x32_bf16 v[82:85], v[198:201], v[228:231], v[82:85]
	v_mfma_f32_16x16x32_bf16 v[72:75], v[174:177], v[236:239], v[72:75]
	v_mfma_f32_16x16x32_bf16 v[64:67], v[198:201], v[236:239], v[64:67]
	s_barrier
; #define PG8_STAGE(bufoff, gbase, voff) do { _Pragma("unroll") for (int _i = 0; _i < 2; ++_i) \
;         __builtin_amdgcn_global_load_lds((const unsigned*)((const char*)(gbase) + (voff)[_i]), (LAS unsigned*)(lds + (bufoff) + ldsw + _i * 8192), 16, 0, 0); } while (0)
; #define PG8_LDA(dst, b, h) do { _Pragma("unroll") for (int m = 0; m < 4; ++m) _Pragma("unroll") for (int k = 0; k < 2; ++k) dst[m][k] = *(const LAS bf16x8*)(lds + PG8_SA(b, h) + aoff + m * 2048 + k * 1024); } while (0)
; #define PG8_MMA(ai, bj, At, Bt) do { __builtin_amdgcn_s_setprio(1); _Pragma("unroll") for (int m = 0; m < 4; ++m) _Pragma("unroll") for (int n = 0; n < 2; ++n) _Pragma("unroll") for (int k = 0; k < 2; ++k) \
;         acc[ai][bj][m][n] = MFMA16(Bt[n][k], At[m][k], acc[ai][bj][m][n]); __builtin_amdgcn_s_setprio(0); } while (0)
; #define PG8_WAIT_V(n) asm volatile("s_waitcnt vmcnt(" #n ")" ::: "memory")
; #define PG8_WAIT_L(n) asm volatile("s_waitcnt lgkmcnt(" #n ")" ::: "memory")
; #define PG8_BAR __builtin_amdgcn_s_barrier()
; #define PG8_SCHED __builtin_amdgcn_sched_barrier(0)
; template <class Epi>
; __device__ __forceinline__ void gemm_phase(LAS unsigned char* lds, const Gemm g, const StaticOrder& S, const Epi& E, int tid_) {
;     ...
;         for (int t = 0; t < nt; t += 2) {
;     ...
;             PG8_WAIT_V(8); PG8_WAIT_L(0); PG8_BAR; PG8_MMA(0, 0, At, B0); PG8_MMA(0, 1, At, B1); PG8_BAR; PG8_SCHED;
;             PG8_LDA(At, 1, 1); PG8_STAGE(PG8_SB(1, 0), b3, voffB); PG8_STAGE(PG8_SB(1, 1), b3 + hsB, voffB); PG8_STAGE(PG8_SA(1, 0), a3, voffA);
;             PG8_WAIT_V(8); PG8_WAIT_L(0); PG8_BAR; PG8_MMA(1, 0, At, B0); PG8_MMA(1, 1, At, B1); PG8_BAR; PG8_SCHED;
;         }
	s_setprio 0
	s_add_i32 s56, s71, s31
	v_lshl_add_u64 v[162:163], v[162:163], 0, s[6:7]
	s_mov_b32 m0, s56
	ds_read_b128 v[202:205], v172 offset:49152
	ds_read_b128 v[206:209], v172 offset:50176
	ds_read_b128 v[216:219], v172 offset:51200
	ds_read_b128 v[220:223], v172 offset:52224
	ds_read_b128 v[224:227], v172 offset:53248
	ds_read_b128 v[228:231], v172 offset:54272
	ds_read_b128 v[232:235], v172 offset:55296
	ds_read_b128 v[236:239], v172 offset:56320
	global_load_lds_dwordx4 v[162:163], off
	s_add_i32 m0, s56, 0x2000
	s_add_u32 s40, s40, 0x40080
	v_lshl_add_u64 v[162:163], v[240:241], 0, s[6:7]
	s_addc_u32 s41, s41, 0
	s_add_i32 s56, s72, s31
	global_load_lds_dwordx4 v[162:163], off
	v_lshl_add_u64 v[162:163], s[40:41], 0, v[150:151]
	s_mov_b32 m0, s56
	s_nop 0
	global_load_lds_dwordx4 v[162:163], off
	v_lshl_add_u64 v[162:163], s[40:41], 0, v[146:147]
	s_add_i32 m0, s56, 0x2000
	s_nop 0
	global_load_lds_dwordx4 v[162:163], off
	v_lshl_add_u64 v[162:163], v[242:243], 0, s[6:7]
	s_mov_b32 m0, s62
	s_nop 0
	global_load_lds_dwordx4 v[162:163], off
	v_lshl_add_u64 v[162:163], v[244:245], 0, s[6:7]
	s_mov_b32 m0, s63
	s_nop 0
	global_load_lds_dwordx4 v[162:163], off
	s_waitcnt vmcnt(8)
	s_waitcnt lgkmcnt(0)
	s_setprio 1
	s_barrier
	v_mfma_f32_16x16x32_bf16 v[60:63], v[130:133], v[202:205], v[60:63]
	v_mfma_f32_16x16x32_bf16 v[52:55], v[138:141], v[202:205], v[52:55]
	v_mfma_f32_16x16x32_bf16 v[44:47], v[130:133], v[216:219], v[44:47]
	v_mfma_f32_16x16x32_bf16 v[36:39], v[138:141], v[216:219], v[36:39]
	v_mfma_f32_16x16x32_bf16 v[28:31], v[130:133], v[224:227], v[28:31]
	v_mfma_f32_16x16x32_bf16 v[20:23], v[138:141], v[224:227], v[20:23]
	v_mfma_f32_16x16x32_bf16 v[12:15], v[130:133], v[232:235], v[12:15]
	v_mfma_f32_16x16x32_bf16 v[4:7], v[138:141], v[232:235], v[4:7]
	v_mfma_f32_16x16x32_bf16 v[60:63], v[134:137], v[206:209], v[60:63]
	v_mfma_f32_16x16x32_bf16 v[52:55], v[142:145], v[206:209], v[52:55]
	v_mfma_f32_16x16x32_bf16 v[44:47], v[134:137], v[220:223], v[44:47]
	v_mfma_f32_16x16x32_bf16 v[36:39], v[142:145], v[220:223], v[36:39]
	v_mfma_f32_16x16x32_bf16 v[28:31], v[134:137], v[228:231], v[28:31]
	v_mfma_f32_16x16x32_bf16 v[20:23], v[142:145], v[228:231], v[20:23]
	v_mfma_f32_16x16x32_bf16 v[12:15], v[134:137], v[236:239], v[12:15]
	v_mfma_f32_16x16x32_bf16 v[4:7], v[142:145], v[236:239], v[4:7]
	v_mfma_f32_16x16x32_bf16 v[56:59], v[158:161], v[202:205], v[56:59]
	v_mfma_f32_16x16x32_bf16 v[48:51], v[178:181], v[202:205], v[48:51]
	v_mfma_f32_16x16x32_bf16 v[40:43], v[158:161], v[216:219], v[40:43]
	v_mfma_f32_16x16x32_bf16 v[32:35], v[178:181], v[216:219], v[32:35]
	v_mfma_f32_16x16x32_bf16 v[24:27], v[158:161], v[224:227], v[24:27]
	v_mfma_f32_16x16x32_bf16 v[16:19], v[178:181], v[224:227], v[16:19]
	v_mfma_f32_16x16x32_bf16 v[8:11], v[158:161], v[232:235], v[8:11]
	v_mfma_f32_16x16x32_bf16 v[0:3], v[178:181], v[232:235], v[0:3]
	v_mfma_f32_16x16x32_bf16 v[56:59], v[174:177], v[206:209], v[56:59]
	v_mfma_f32_16x16x32_bf16 v[48:51], v[198:201], v[206:209], v[48:51]
	v_mfma_f32_16x16x32_bf16 v[40:43], v[174:177], v[220:223], v[40:43]
	v_mfma_f32_16x16x32_bf16 v[32:35], v[198:201], v[220:223], v[32:35]
	v_mfma_f32_16x16x32_bf16 v[24:27], v[174:177], v[228:231], v[24:27]
	v_mfma_f32_16x16x32_bf16 v[16:19], v[198:201], v[228:231], v[16:19]
	v_mfma_f32_16x16x32_bf16 v[8:11], v[174:177], v[236:239], v[8:11]
	v_mfma_f32_16x16x32_bf16 v[0:3], v[198:201], v[236:239], v[0:3]
	s_barrier
	s_setprio 0
	s_add_u32 s28, s28, 0x100
	s_addc_u32 s29, s29, 0
	s_add_u32 s68, s68, 0x100
	s_addc_u32 s69, s69, 0
	s_cmp_ge_i32 s70, s30
	s_mov_b32 s40, s70
	s_cbranch_scc0 .LBB0_85
	s_and_b64 vcc, exec, s[48:49]
	s_cbranch_vccz .LBB0_88

; #define PG8_STAGE(bufoff, gbase, voff) do { _Pragma("unroll") for (int _i = 0; _i < 2; ++_i) \
;         __builtin_amdgcn_global_load_lds((const unsigned*)((const char*)(gbase) + (voff)[_i]), (LAS unsigned*)(lds + (bufoff) + ldsw + _i * 8192), 16, 0, 0); } while (0)
; #define PG8_LDA(dst, b, h) do { _Pragma("unroll") for (int m = 0; m < 4; ++m) _Pragma("unroll") for (int k = 0; k < 2; ++k) dst[m][k] = *(const LAS bf16x8*)(lds + PG8_SA(b, h) + aoff + m * 2048 + k * 1024); } while (0)
; #define PG8_LDB(dst, b, h) do { _Pragma("unroll") for (int n = 0; n < 2; ++n) _Pragma("unroll") for (int k = 0; k < 2; ++k) dst[n][k] = *(const LAS bf16x8*)(lds + PG8_SB(b, h) + boff + n * 2048 + k * 1024); } while (0)
; #define PG8_MMA(ai, bj, At, Bt) do { __builtin_amdgcn_s_setprio(1); _Pragma("unroll") for (int m = 0; m < 4; ++m) _Pragma("unroll") for (int n = 0; n < 2; ++n) _Pragma("unroll") for (int k = 0; k < 2; ++k) \
;         acc[ai][bj][m][n] = MFMA16(Bt[n][k], At[m][k], acc[ai][bj][m][n]); __builtin_amdgcn_s_setprio(0); } while (0)
; #define PG8_WAIT_V(n) asm volatile("s_waitcnt vmcnt(" #n ")" ::: "memory")
; #define PG8_WAIT_L(n) asm volatile("s_waitcnt lgkmcnt(" #n ")" ::: "memory")
; #define PG8_BAR __builtin_amdgcn_s_barrier()
; #define PG8_SCHED __builtin_amdgcn_sched_barrier(0)
; template <class Epi>
; __device__ __forceinline__ void gemm_phase(LAS unsigned char* lds, const Gemm g, const StaticOrder& S, const Epi& E, int tid_) {
;     ...
;             const bool last = (t == nt - 2);
;             const char* a1 = cA + (size_t)(t + 1) * kstep;
;             const char* a2 = last ? nA : cA + (size_t)(t + 2) * kstep; const char* b2 = last ? nB : cB + (size_t)(t + 2) * kstep;
;             const char* a3 = a2 + kstep; const char* b3 = b2 + kstep;
;             PG8_LDB(B0, 0, 0); PG8_LDB(B1, 0, 1); PG8_SCHED; PG8_LDA(At, 0, 0); PG8_STAGE(PG8_SA(1, 1), a1 + hsA, voffA);
;             PG8_WAIT_V(8); PG8_WAIT_L(0); PG8_BAR; PG8_MMA(0, 0, At, B0); PG8_MMA(0, 1, At, B1); PG8_BAR; PG8_SCHED;
;             PG8_LDA(At, 0, 1); PG8_STAGE(PG8_SB(0, 0), b2, voffB); PG8_STAGE(PG8_SB(0, 1), b2 + hsB, voffB); PG8_STAGE(PG8_SA(0, 0), a2, voffA);
;             PG8_WAIT_V(8); PG8_WAIT_L(0); PG8_BAR; PG8_MMA(1, 0, At, B0); PG8_MMA(1, 1, At, B1); PG8_BAR; PG8_SCHED;
.LBB0_172:
	s_add_i32 s74, s40, 2
	s_add_u32 s41, s28, 0xfffc0080
	s_addc_u32 s60, s29, -1
	s_add_i32 s75, 0, 0x10000
	s_cmp_eq_u32 s68, s40
	s_cselect_b32 s61, s22, s60
	s_cselect_b32 s60, s23, s41
	s_cselect_b32 s41, s49, s73
	s_cselect_b32 s40, s55, s72
	s_add_i32 s78, 0, 0x14000
	v_add_u32_e32 v142, s75, v165
	v_add_u32_e32 v162, s78, v165
	ds_read_b128 v[130:133], v142
	ds_read_b128 v[134:137], v142 offset:1024
	ds_read_b128 v[138:141], v142 offset:2048
	ds_read_b128 v[142:145], v142 offset:3072
	ds_read_b128 v[158:161], v162
	ds_read_b128 v[174:177], v162 offset:1024
	ds_read_b128 v[178:181], v162 offset:2048
	ds_read_b128 v[198:201], v162 offset:3072
	v_lshl_add_u64 v[162:163], s[28:29], 0, v[154:155]
	s_add_i32 m0, s43, 0xc000
	ds_read_b128 v[202:205], v172
	ds_read_b128 v[206:209], v172 offset:1024
	ds_read_b128 v[216:219], v172 offset:2048
	ds_read_b128 v[220:223], v172 offset:3072
	ds_read_b128 v[224:227], v172 offset:4096
	ds_read_b128 v[228:231], v172 offset:5120
	ds_read_b128 v[232:235], v172 offset:6144
	ds_read_b128 v[236:239], v172 offset:7168
	global_load_lds_dwordx4 v[162:163], off
	v_lshl_add_u64 v[162:163], s[28:29], 0, v[156:157]
	s_add_i32 m0, s43, 0xe000
	s_nop 0
	global_load_lds_dwordx4 v[162:163], off
	s_waitcnt vmcnt(8)
	s_waitcnt lgkmcnt(0)
	s_setprio 1
	s_barrier
	v_mfma_f32_16x16x32_bf16 v[126:129], v[130:133], v[202:205], v[126:129]
	v_mfma_f32_16x16x32_bf16 v[122:125], v[138:141], v[202:205], v[122:125]
	v_mfma_f32_16x16x32_bf16 v[110:113], v[130:133], v[216:219], v[110:113]
	v_mfma_f32_16x16x32_bf16 v[106:109], v[138:141], v[216:219], v[106:109]
	v_mfma_f32_16x16x32_bf16 v[94:97], v[130:133], v[224:227], v[94:97]
	v_mfma_f32_16x16x32_bf16 v[90:93], v[138:141], v[224:227], v[90:93]
	v_mfma_f32_16x16x32_bf16 v[76:79], v[130:133], v[232:235], v[76:79]
	v_mfma_f32_16x16x32_bf16 v[72:75], v[138:141], v[232:235], v[72:75]
	v_mfma_f32_16x16x32_bf16 v[126:129], v[134:137], v[206:209], v[126:129]
	v_mfma_f32_16x16x32_bf16 v[122:125], v[142:145], v[206:209], v[122:125]
	v_mfma_f32_16x16x32_bf16 v[110:113], v[134:137], v[220:223], v[110:113]
	v_mfma_f32_16x16x32_bf16 v[106:109], v[142:145], v[220:223], v[106:109]
	v_mfma_f32_16x16x32_bf16 v[94:97], v[134:137], v[228:231], v[94:97]
	v_mfma_f32_16x16x32_bf16 v[90:93], v[142:145], v[228:231], v[90:93]
	v_mfma_f32_16x16x32_bf16 v[76:79], v[134:137], v[236:239], v[76:79]
	v_mfma_f32_16x16x32_bf16 v[72:75], v[142:145], v[236:239], v[72:75]
	v_mfma_f32_16x16x32_bf16 v[118:121], v[158:161], v[202:205], v[118:121]
	v_mfma_f32_16x16x32_bf16 v[114:117], v[178:181], v[202:205], v[114:117]
	v_mfma_f32_16x16x32_bf16 v[102:105], v[158:161], v[216:219], v[102:105]
	v_mfma_f32_16x16x32_bf16 v[98:101], v[178:181], v[216:219], v[98:101]
	v_mfma_f32_16x16x32_bf16 v[86:89], v[158:161], v[224:227], v[86:89]
	v_mfma_f32_16x16x32_bf16 v[82:85], v[178:181], v[224:227], v[82:85]
	v_mfma_f32_16x16x32_bf16 v[68:71], v[158:161], v[232:235], v[68:71]
	v_mfma_f32_16x16x32_bf16 v[64:67], v[178:181], v[232:235], v[64:67]
	v_mfma_f32_16x16x32_bf16 v[118:121], v[174:177], v[206:209], v[118:121]
	v_mfma_f32_16x16x32_bf16 v[114:117], v[198:201], v[206:209], v[114:117]
	v_mfma_f32_16x16x32_bf16 v[102:105], v[174:177], v[220:223], v[102:105]
	v_mfma_f32_16x16x32_bf16 v[98:101], v[198:201], v[220:223], v[98:101]
	v_mfma_f32_16x16x32_bf16 v[86:89], v[174:177], v[228:231], v[86:89]
	v_mfma_f32_16x16x32_bf16 v[82:85], v[198:201], v[228:231], v[82:85]
	v_mfma_f32_16x16x32_bf16 v[68:71], v[174:177], v[236:239], v[68:71]
	v_mfma_f32_16x16x32_bf16 v[64:67], v[198:201], v[236:239], v[64:67]
	s_barrier
	s_setprio 0
	s_add_i32 s75, s75, s31
	v_lshl_add_u64 v[162:163], s[40:41], 0, v[148:149]
	s_mov_b32 m0, s75
	ds_read_b128 v[202:205], v172 offset:16384
	ds_read_b128 v[206:209], v172 offset:17408
	ds_read_b128 v[216:219], v172 offset:18432
	ds_read_b128 v[220:223], v172 offset:19456
	ds_read_b128 v[224:227], v172 offset:20480
	ds_read_b128 v[228:231], v172 offset:21504
	ds_read_b128 v[232:235], v172 offset:22528
	ds_read_b128 v[236:239], v172 offset:23552
	global_load_lds_dwordx4 v[162:163], off
	s_add_i32 m0, s75, 0x2000
	s_add_u32 s76, s40, 0x40000
	v_lshl_add_u64 v[240:241], s[40:41], 0, v[152:153]
	s_addc_u32 s77, s41, 0
	s_add_i32 s75, s78, s31
	global_load_lds_dwordx4 v[240:241], off
	v_lshl_add_u64 v[242:243], s[76:77], 0, v[148:149]
	s_mov_b32 m0, s75
	v_lshl_add_u64 v[244:245], s[60:61], 0, v[150:151]
	global_load_lds_dwordx4 v[242:243], off
	v_lshl_add_u64 v[242:243], s[76:77], 0, v[152:153]
	s_add_i32 m0, s75, 0x2000
	s_nop 0
	global_load_lds_dwordx4 v[242:243], off
	v_lshl_add_u64 v[242:243], s[60:61], 0, v[146:147]
	s_mov_b32 m0, s43
	s_nop 0
	global_load_lds_dwordx4 v[242:243], off
	s_mov_b32 m0, s62
	s_nop 0
	global_load_lds_dwordx4 v[244:245], off
	s_waitcnt vmcnt(8)
	s_waitcnt lgkmcnt(0)
	s_setprio 1
	s_barrier
; #define PG8_STAGE(bufoff, gbase, voff) do { _Pragma("unroll") for (int _i = 0; _i < 2; ++_i) \
;         __builtin_amdgcn_global_load_lds((const unsigned*)((const char*)(gbase) + (voff)[_i]), (LAS unsigned*)(lds + (bufoff) + ldsw + _i * 8192), 16, 0, 0); } while (0)
; #define PG8_LDA(dst, b, h) do { _Pragma("unroll") for (int m = 0; m < 4; ++m) _Pragma("unroll") for (int k = 0; k < 2; ++k) dst[m][k] = *(const LAS bf16x8*)(lds + PG8_SA(b, h) + aoff + m * 2048 + k * 1024); } while (0)
; #define PG8_LDB(dst, b, h) do { _Pragma("unroll") for (int n = 0; n < 2; ++n) _Pragma("unroll") for (int k = 0; k < 2; ++k) dst[n][k] = *(const LAS bf16x8*)(lds + PG8_SB(b, h) + boff + n * 2048 + k * 1024); } while (0)
; #define PG8_MMA(ai, bj, At, Bt) do { __builtin_amdgcn_s_setprio(1); _Pragma("unroll") for (int m = 0; m < 4; ++m) _Pragma("unroll") for (int n = 0; n < 2; ++n) _Pragma("unroll") for (int k = 0; k < 2; ++k) \
;         acc[ai][bj][m][n] = MFMA16(Bt[n][k], At[m][k], acc[ai][bj][m][n]); __builtin_amdgcn_s_setprio(0); } while (0)
; #define PG8_WAIT_V(n) asm volatile("s_waitcnt vmcnt(" #n ")" ::: "memory")
; #define PG8_WAIT_L(n) asm volatile("s_waitcnt lgkmcnt(" #n ")" ::: "memory")
; #define PG8_BAR __builtin_amdgcn_s_barrier()
; #define PG8_SCHED __builtin_amdgcn_sched_barrier(0)
; template <class Epi>
; __device__ __forceinline__ void gemm_phase(LAS unsigned char* lds, const Gemm g, const StaticOrder& S, const Epi& E, int tid_) {
;     ...
;             PG8_WAIT_V(8); PG8_WAIT_L(0); PG8_BAR; PG8_MMA(1, 0, At, B0); PG8_MMA(1, 1, At, B1); PG8_BAR; PG8_SCHED;
;             PG8_LDB(B0, 1, 0); PG8_LDB(B1, 1, 1); PG8_SCHED; PG8_LDA(At, 1, 0); PG8_STAGE(PG8_SA(0, 1), a2 + hsA, voffA);
;             PG8_WAIT_V(8); PG8_WAIT_L(0); PG8_BAR; PG8_MMA(0, 0, At, B0); PG8_MMA(0, 1, At, B1); PG8_BAR; PG8_SCHED;
	v_mfma_f32_16x16x32_bf16 v[60:63], v[130:133], v[202:205], v[60:63]
	v_mfma_f32_16x16x32_bf16 v[56:59], v[138:141], v[202:205], v[56:59]
	v_mfma_f32_16x16x32_bf16 v[44:47], v[130:133], v[216:219], v[44:47]
	v_mfma_f32_16x16x32_bf16 v[40:43], v[138:141], v[216:219], v[40:43]
	v_mfma_f32_16x16x32_bf16 v[28:31], v[130:133], v[224:227], v[28:31]
	v_mfma_f32_16x16x32_bf16 v[24:27], v[138:141], v[224:227], v[24:27]
	v_mfma_f32_16x16x32_bf16 v[12:15], v[130:133], v[232:235], v[12:15]
	v_mfma_f32_16x16x32_bf16 v[8:11], v[138:141], v[232:235], v[8:11]
	v_mfma_f32_16x16x32_bf16 v[60:63], v[134:137], v[206:209], v[60:63]
	v_mfma_f32_16x16x32_bf16 v[56:59], v[142:145], v[206:209], v[56:59]
	v_mfma_f32_16x16x32_bf16 v[44:47], v[134:137], v[220:223], v[44:47]
	v_mfma_f32_16x16x32_bf16 v[40:43], v[142:145], v[220:223], v[40:43]
	v_mfma_f32_16x16x32_bf16 v[28:31], v[134:137], v[228:231], v[28:31]
	v_mfma_f32_16x16x32_bf16 v[24:27], v[142:145], v[228:231], v[24:27]
	v_mfma_f32_16x16x32_bf16 v[12:15], v[134:137], v[236:239], v[12:15]
	v_mfma_f32_16x16x32_bf16 v[8:11], v[142:145], v[236:239], v[8:11]
	v_mfma_f32_16x16x32_bf16 v[52:55], v[158:161], v[202:205], v[52:55]
	v_mfma_f32_16x16x32_bf16 v[48:51], v[178:181], v[202:205], v[48:51]
	v_mfma_f32_16x16x32_bf16 v[36:39], v[158:161], v[216:219], v[36:39]
	v_mfma_f32_16x16x32_bf16 v[32:35], v[178:181], v[216:219], v[32:35]
	v_mfma_f32_16x16x32_bf16 v[20:23], v[158:161], v[224:227], v[20:23]
	v_mfma_f32_16x16x32_bf16 v[16:19], v[178:181], v[224:227], v[16:19]
	v_mfma_f32_16x16x32_bf16 v[4:7], v[158:161], v[232:235], v[4:7]
	v_mfma_f32_16x16x32_bf16 v[0:3], v[178:181], v[232:235], v[0:3]
	v_mfma_f32_16x16x32_bf16 v[52:55], v[174:177], v[206:209], v[52:55]
	v_mfma_f32_16x16x32_bf16 v[48:51], v[198:201], v[206:209], v[48:51]
	v_mfma_f32_16x16x32_bf16 v[36:39], v[174:177], v[220:223], v[36:39]
	v_mfma_f32_16x16x32_bf16 v[32:35], v[198:201], v[220:223], v[32:35]
	v_mfma_f32_16x16x32_bf16 v[20:23], v[174:177], v[228:231], v[20:23]
	v_mfma_f32_16x16x32_bf16 v[16:19], v[198:201], v[228:231], v[16:19]
	v_mfma_f32_16x16x32_bf16 v[4:7], v[174:177], v[236:239], v[4:7]
	v_mfma_f32_16x16x32_bf16 v[0:3], v[198:201], v[236:239], v[0:3]
	s_barrier
	s_setprio 0
	s_add_i32 s75, 0, 0x18000
	s_add_i32 s76, 0, 0x1c000
	v_add_u32_e32 v142, s75, v165
	v_add_u32_e32 v173, s76, v165
	ds_read_b128 v[130:133], v142
	ds_read_b128 v[134:137], v142 offset:1024
	ds_read_b128 v[138:141], v142 offset:2048
	ds_read_b128 v[142:145], v142 offset:3072
	ds_read_b128 v[158:161], v173
	ds_read_b128 v[174:177], v173 offset:1024
	ds_read_b128 v[178:181], v173 offset:2048
	ds_read_b128 v[198:201], v173 offset:3072
	s_add_u32 s60, s60, 0x40000
	s_addc_u32 s61, s61, 0
	s_mov_b32 m0, s63
	v_lshl_add_u64 v[246:247], s[60:61], 0, v[146:147]
	ds_read_b128 v[202:205], v172 offset:32768
	ds_read_b128 v[206:209], v172 offset:33792
	ds_read_b128 v[216:219], v172 offset:34816
	ds_read_b128 v[220:223], v172 offset:35840
	ds_read_b128 v[224:227], v172 offset:36864
	ds_read_b128 v[228:231], v172 offset:37888
	ds_read_b128 v[232:235], v172 offset:38912
	ds_read_b128 v[236:239], v172 offset:39936
	global_load_lds_dwordx4 v[246:247], off
	v_lshl_add_u64 v[246:247], s[60:61], 0, v[150:151]
	s_mov_b32 m0, s64
	s_nop 0
	global_load_lds_dwordx4 v[246:247], off
	s_waitcnt vmcnt(8)
	s_waitcnt lgkmcnt(0)
	s_setprio 1
	s_barrier
	v_mfma_f32_16x16x32_bf16 v[126:129], v[130:133], v[202:205], v[126:129]
	v_mfma_f32_16x16x32_bf16 v[122:125], v[138:141], v[202:205], v[122:125]
	v_mfma_f32_16x16x32_bf16 v[110:113], v[130:133], v[216:219], v[110:113]
	v_mfma_f32_16x16x32_bf16 v[106:109], v[138:141], v[216:219], v[106:109]
	v_mfma_f32_16x16x32_bf16 v[94:97], v[130:133], v[224:227], v[94:97]
	v_mfma_f32_16x16x32_bf16 v[90:93], v[138:141], v[224:227], v[90:93]
	v_mfma_f32_16x16x32_bf16 v[76:79], v[130:133], v[232:235], v[76:79]
	v_mfma_f32_16x16x32_bf16 v[72:75], v[138:141], v[232:235], v[72:75]
	v_mfma_f32_16x16x32_bf16 v[126:129], v[134:137], v[206:209], v[126:129]
	v_mfma_f32_16x16x32_bf16 v[122:125], v[142:145], v[206:209], v[122:125]
	v_mfma_f32_16x16x32_bf16 v[110:113], v[134:137], v[220:223], v[110:113]
	v_mfma_f32_16x16x32_bf16 v[106:109], v[142:145], v[220:223], v[106:109]
	v_mfma_f32_16x16x32_bf16 v[94:97], v[134:137], v[228:231], v[94:97]
	v_mfma_f32_16x16x32_bf16 v[90:93], v[142:145], v[228:231], v[90:93]
	v_mfma_f32_16x16x32_bf16 v[76:79], v[134:137], v[236:239], v[76:79]
	v_mfma_f32_16x16x32_bf16 v[72:75], v[142:145], v[236:239], v[72:75]
	v_mfma_f32_16x16x32_bf16 v[118:121], v[158:161], v[202:205], v[118:121]
	v_mfma_f32_16x16x32_bf16 v[114:117], v[178:181], v[202:205], v[114:117]
	v_mfma_f32_16x16x32_bf16 v[102:105], v[158:161], v[216:219], v[102:105]
	v_mfma_f32_16x16x32_bf16 v[98:101], v[178:181], v[216:219], v[98:101]
	v_mfma_f32_16x16x32_bf16 v[86:89], v[158:161], v[224:227], v[86:89]
	v_mfma_f32_16x16x32_bf16 v[82:85], v[178:181], v[224:227], v[82:85]
	v_mfma_f32_16x16x32_bf16 v[68:71], v[158:161], v[232:235], v[68:71]
	v_mfma_f32_16x16x32_bf16 v[64:67], v[178:181], v[232:235], v[64:67]
	v_mfma_f32_16x16x32_bf16 v[118:121], v[174:177], v[206:209], v[118:121]
	v_mfma_f32_16x16x32_bf16 v[114:117], v[198:201], v[206:209], v[114:117]
	v_mfma_f32_16x16x32_bf16 v[102:105], v[174:177], v[220:223], v[102:105]
	v_mfma_f32_16x16x32_bf16 v[98:101], v[198:201], v[220:223], v[98:101]
	v_mfma_f32_16x16x32_bf16 v[86:89], v[174:177], v[228:231], v[86:89]
	v_mfma_f32_16x16x32_bf16 v[82:85], v[198:201], v[228:231], v[82:85]
	v_mfma_f32_16x16x32_bf16 v[68:71], v[174:177], v[236:239], v[68:71]
	v_mfma_f32_16x16x32_bf16 v[64:67], v[198:201], v[236:239], v[64:67]
	s_barrier
; #define PG8_STAGE(bufoff, gbase, voff) do { _Pragma("unroll") for (int _i = 0; _i < 2; ++_i) \
;         __builtin_amdgcn_global_load_lds((const unsigned*)((const char*)(gbase) + (voff)[_i]), (LAS unsigned*)(lds + (bufoff) + ldsw + _i * 8192), 16, 0, 0); } while (0)
; #define PG8_LDA(dst, b, h) do { _Pragma("unroll") for (int m = 0; m < 4; ++m) _Pragma("unroll") for (int k = 0; k < 2; ++k) dst[m][k] = *(const LAS bf16x8*)(lds + PG8_SA(b, h) + aoff + m * 2048 + k * 1024); } while (0)
; #define PG8_MMA(ai, bj, At, Bt) do { __builtin_amdgcn_s_setprio(1); _Pragma("unroll") for (int m = 0; m < 4; ++m) _Pragma("unroll") for (int n = 0; n < 2; ++n) _Pragma("unroll") for (int k = 0; k < 2; ++k) \
;         acc[ai][bj][m][n] = MFMA16(Bt[n][k], At[m][k], acc[ai][bj][m][n]); __builtin_amdgcn_s_setprio(0); } while (0)
; #define PG8_WAIT_V(n) asm volatile("s_waitcnt vmcnt(" #n ")" ::: "memory")
; #define PG8_WAIT_L(n) asm volatile("s_waitcnt lgkmcnt(" #n ")" ::: "memory")
; #define PG8_BAR __builtin_amdgcn_s_barrier()
; #define PG8_SCHED __builtin_amdgcn_sched_barrier(0)
; template <class Epi>
; __device__ __forceinline__ void gemm_phase(LAS unsigned char* lds, const Gemm g, const StaticOrder& S, const Epi& E, int tid_) {
;     ...
;             PG8_LDA(At, 1, 1); PG8_STAGE(PG8_SB(1, 0), b3, voffB); PG8_STAGE(PG8_SB(1, 1), b3 + hsB, voffB); PG8_STAGE(PG8_SA(1, 0), a3, voffA);
;             PG8_WAIT_V(8); PG8_WAIT_L(0); PG8_BAR; PG8_MMA(1, 0, At, B0); PG8_MMA(1, 1, At, B1); PG8_BAR; PG8_SCHED;
;         }
	s_setprio 0
	s_add_i32 s60, s75, s31
	v_lshl_add_u64 v[162:163], v[162:163], 0, s[6:7]
	s_mov_b32 m0, s60
	ds_read_b128 v[202:205], v172 offset:49152
	ds_read_b128 v[206:209], v172 offset:50176
	ds_read_b128 v[216:219], v172 offset:51200
	ds_read_b128 v[220:223], v172 offset:52224
	ds_read_b128 v[224:227], v172 offset:53248
	ds_read_b128 v[228:231], v172 offset:54272
	ds_read_b128 v[232:235], v172 offset:55296
	ds_read_b128 v[236:239], v172 offset:56320
	global_load_lds_dwordx4 v[162:163], off
	s_add_i32 m0, s60, 0x2000
	s_add_u32 s40, s40, 0x40080
	v_lshl_add_u64 v[162:163], v[240:241], 0, s[6:7]
	s_addc_u32 s41, s41, 0
	s_add_i32 s60, s76, s31
	global_load_lds_dwordx4 v[162:163], off
	v_lshl_add_u64 v[162:163], s[40:41], 0, v[148:149]
	s_mov_b32 m0, s60
	s_nop 0
	global_load_lds_dwordx4 v[162:163], off
	v_lshl_add_u64 v[162:163], s[40:41], 0, v[152:153]
	s_add_i32 m0, s60, 0x2000
	s_nop 0
	global_load_lds_dwordx4 v[162:163], off
	v_lshl_add_u64 v[162:163], v[242:243], 0, s[6:7]
	s_mov_b32 m0, s65
	s_nop 0
	global_load_lds_dwordx4 v[162:163], off
	v_lshl_add_u64 v[162:163], v[244:245], 0, s[6:7]
	s_mov_b32 m0, s66
	s_nop 0
	global_load_lds_dwordx4 v[162:163], off
	s_waitcnt vmcnt(8)
	s_waitcnt lgkmcnt(0)
	s_setprio 1
	s_barrier
	v_mfma_f32_16x16x32_bf16 v[60:63], v[130:133], v[202:205], v[60:63]
	v_mfma_f32_16x16x32_bf16 v[56:59], v[138:141], v[202:205], v[56:59]
	v_mfma_f32_16x16x32_bf16 v[44:47], v[130:133], v[216:219], v[44:47]
	v_mfma_f32_16x16x32_bf16 v[40:43], v[138:141], v[216:219], v[40:43]
	v_mfma_f32_16x16x32_bf16 v[28:31], v[130:133], v[224:227], v[28:31]
	v_mfma_f32_16x16x32_bf16 v[24:27], v[138:141], v[224:227], v[24:27]
	v_mfma_f32_16x16x32_bf16 v[12:15], v[130:133], v[232:235], v[12:15]
	v_mfma_f32_16x16x32_bf16 v[8:11], v[138:141], v[232:235], v[8:11]
	v_mfma_f32_16x16x32_bf16 v[60:63], v[134:137], v[206:209], v[60:63]
	v_mfma_f32_16x16x32_bf16 v[56:59], v[142:145], v[206:209], v[56:59]
	v_mfma_f32_16x16x32_bf16 v[44:47], v[134:137], v[220:223], v[44:47]
	v_mfma_f32_16x16x32_bf16 v[40:43], v[142:145], v[220:223], v[40:43]
	v_mfma_f32_16x16x32_bf16 v[28:31], v[134:137], v[228:231], v[28:31]
	v_mfma_f32_16x16x32_bf16 v[24:27], v[142:145], v[228:231], v[24:27]
	v_mfma_f32_16x16x32_bf16 v[12:15], v[134:137], v[236:239], v[12:15]
	v_mfma_f32_16x16x32_bf16 v[8:11], v[142:145], v[236:239], v[8:11]
	v_mfma_f32_16x16x32_bf16 v[52:55], v[158:161], v[202:205], v[52:55]
	v_mfma_f32_16x16x32_bf16 v[48:51], v[178:181], v[202:205], v[48:51]
	v_mfma_f32_16x16x32_bf16 v[36:39], v[158:161], v[216:219], v[36:39]
	v_mfma_f32_16x16x32_bf16 v[32:35], v[178:181], v[216:219], v[32:35]
	v_mfma_f32_16x16x32_bf16 v[20:23], v[158:161], v[224:227], v[20:23]
	v_mfma_f32_16x16x32_bf16 v[16:19], v[178:181], v[224:227], v[16:19]
	v_mfma_f32_16x16x32_bf16 v[4:7], v[158:161], v[232:235], v[4:7]
	v_mfma_f32_16x16x32_bf16 v[0:3], v[178:181], v[232:235], v[0:3]
	v_mfma_f32_16x16x32_bf16 v[52:55], v[174:177], v[206:209], v[52:55]
	v_mfma_f32_16x16x32_bf16 v[48:51], v[198:201], v[206:209], v[48:51]
	v_mfma_f32_16x16x32_bf16 v[36:39], v[174:177], v[220:223], v[36:39]
	v_mfma_f32_16x16x32_bf16 v[32:35], v[198:201], v[220:223], v[32:35]
	v_mfma_f32_16x16x32_bf16 v[20:23], v[174:177], v[228:231], v[20:23]
	v_mfma_f32_16x16x32_bf16 v[16:19], v[198:201], v[228:231], v[16:19]
	v_mfma_f32_16x16x32_bf16 v[4:7], v[174:177], v[236:239], v[4:7]
	v_mfma_f32_16x16x32_bf16 v[0:3], v[198:201], v[236:239], v[0:3]
	s_barrier
	s_setprio 0
	s_add_u32 s28, s28, 0x100
	s_addc_u32 s29, s29, 0
	s_add_u32 s72, s72, 0x100
	s_addc_u32 s73, s73, 0
	s_cmp_ge_i32 s74, s18
	s_mov_b32 s40, s74
	s_cbranch_scc0 .LBB0_172
	s_and_b64 vcc, exec, s[52:53]
	s_cbranch_vccz .LBB0_175

; #define PG8_STAGE(bufoff, gbase, voff) do { _Pragma("unroll") for (int _i = 0; _i < 2; ++_i) \
;         __builtin_amdgcn_global_load_lds((const unsigned*)((const char*)(gbase) + (voff)[_i]), (LAS unsigned*)(lds + (bufoff) + ldsw + _i * 8192), 16, 0, 0); } while (0)
; #define PG8_LDA(dst, b, h) do { _Pragma("unroll") for (int m = 0; m < 4; ++m) _Pragma("unroll") for (int k = 0; k < 2; ++k) dst[m][k] = *(const LAS bf16x8*)(lds + PG8_SA(b, h) + aoff + m * 2048 + k * 1024); } while (0)
; #define PG8_LDB(dst, b, h) do { _Pragma("unroll") for (int n = 0; n < 2; ++n) _Pragma("unroll") for (int k = 0; k < 2; ++k) dst[n][k] = *(const LAS bf16x8*)(lds + PG8_SB(b, h) + boff + n * 2048 + k * 1024); } while (0)
; #define PG8_MMA(ai, bj, At, Bt) do { __builtin_amdgcn_s_setprio(1); _Pragma("unroll") for (int m = 0; m < 4; ++m) _Pragma("unroll") for (int n = 0; n < 2; ++n) _Pragma("unroll") for (int k = 0; k < 2; ++k) \
;         acc[ai][bj][m][n] = MFMA16(Bt[n][k], At[m][k], acc[ai][bj][m][n]); __builtin_amdgcn_s_setprio(0); } while (0)
; #define PG8_WAIT_V(n) asm volatile("s_waitcnt vmcnt(" #n ")" ::: "memory")
; #define PG8_WAIT_L(n) asm volatile("s_waitcnt lgkmcnt(" #n ")" ::: "memory")
; #define PG8_BAR __builtin_amdgcn_s_barrier()
; #define PG8_SCHED __builtin_amdgcn_sched_barrier(0)
; template <class Epi>
; __device__ __forceinline__ void gemm_phase(LAS unsigned char* lds, const Gemm g, const StaticOrder& S, const Epi& E, int tid_) {
;     ...
;             const bool last = (t == nt - 2);
;             const char* a1 = cA + (size_t)(t + 1) * kstep;
;             const char* a2 = last ? nA : cA + (size_t)(t + 2) * kstep; const char* b2 = last ? nB : cB + (size_t)(t + 2) * kstep;
;             const char* a3 = a2 + kstep; const char* b3 = b2 + kstep;
;             PG8_LDB(B0, 0, 0); PG8_LDB(B1, 0, 1); PG8_SCHED; PG8_LDA(At, 0, 0); PG8_STAGE(PG8_SA(1, 1), a1 + hsA, voffA);
;             PG8_WAIT_V(8); PG8_WAIT_L(0); PG8_BAR; PG8_MMA(0, 0, At, B0); PG8_MMA(0, 1, At, B1); PG8_BAR; PG8_SCHED;
;             PG8_LDA(At, 0, 1); PG8_STAGE(PG8_SB(0, 0), b2, voffB); PG8_STAGE(PG8_SB(0, 1), b2 + hsB, voffB); PG8_STAGE(PG8_SA(0, 0), a2, voffA);
.LBB0_320:
	s_add_i32 s81, s66, 2
	s_add_u32 s67, s64, 0xfffc0080
	s_addc_u32 s68, s65, -1
	s_add_i32 s82, 0, 0x10000
	s_cmp_eq_u32 s78, s66
	s_cselect_b32 s69, s22, s68
	s_cselect_b32 s68, s23, s67
	s_cselect_b32 s67, s29, s80
	s_cselect_b32 s66, s57, s59
	s_add_i32 s91, 0, 0x14000
	v_add_u32_e32 v94, s82, v81
	v_add_u32_e32 v150, s91, v81
	ds_read_b128 v[76:79], v94
	ds_read_b128 v[82:85], v94 offset:1024
	ds_read_b128 v[90:93], v94 offset:2048
	ds_read_b128 v[94:97], v94 offset:3072
	ds_read_b128 v[98:101], v150
	ds_read_b128 v[114:117], v150 offset:1024
	ds_read_b128 v[134:137], v150 offset:2048
	ds_read_b128 v[150:153], v150 offset:3072
	v_lshl_add_u64 v[232:233], s[64:65], 0, v[206:207]
	s_add_i32 m0, s72, 0xc000
	ds_read_b128 v[162:165], v218
	ds_read_b128 v[166:169], v218 offset:1024
	ds_read_b128 v[170:173], v218 offset:2048
	ds_read_b128 v[174:177], v218 offset:3072
	ds_read_b128 v[178:181], v218 offset:4096
	ds_read_b128 v[220:223], v218 offset:5120
	ds_read_b128 v[224:227], v218 offset:6144
	ds_read_b128 v[228:231], v218 offset:7168
	global_load_lds_dwordx4 v[232:233], off
	v_lshl_add_u64 v[232:233], s[64:65], 0, v[208:209]
	s_add_i32 m0, s72, 0xe000
	s_nop 0
	global_load_lds_dwordx4 v[232:233], off
	s_waitcnt vmcnt(8)
	s_waitcnt lgkmcnt(0)
	s_setprio 1
	s_barrier
	v_mfma_f32_16x16x32_bf16 v[158:161], v[76:79], v[162:165], v[158:161]
	v_mfma_f32_16x16x32_bf16 v[146:149], v[90:93], v[162:165], v[146:149]
	v_mfma_f32_16x16x32_bf16 v[138:141], v[76:79], v[170:173], v[138:141]
	v_mfma_f32_16x16x32_bf16 v[126:129], v[90:93], v[170:173], v[126:129]
	v_mfma_f32_16x16x32_bf16 v[118:121], v[76:79], v[178:181], v[118:121]
	v_mfma_f32_16x16x32_bf16 v[106:109], v[90:93], v[178:181], v[106:109]
	v_mfma_f32_16x16x32_bf16 v[86:89], v[76:79], v[224:227], v[86:89]
	v_mfma_f32_16x16x32_bf16 v[68:71], v[90:93], v[224:227], v[68:71]
	v_mfma_f32_16x16x32_bf16 v[158:161], v[82:85], v[166:169], v[158:161]
	v_mfma_f32_16x16x32_bf16 v[146:149], v[94:97], v[166:169], v[146:149]
	v_mfma_f32_16x16x32_bf16 v[138:141], v[82:85], v[174:177], v[138:141]
	v_mfma_f32_16x16x32_bf16 v[126:129], v[94:97], v[174:177], v[126:129]
	v_mfma_f32_16x16x32_bf16 v[118:121], v[82:85], v[220:223], v[118:121]
	v_mfma_f32_16x16x32_bf16 v[106:109], v[94:97], v[220:223], v[106:109]
	v_mfma_f32_16x16x32_bf16 v[86:89], v[82:85], v[228:231], v[86:89]
	v_mfma_f32_16x16x32_bf16 v[68:71], v[94:97], v[228:231], v[68:71]
	v_mfma_f32_16x16x32_bf16 v[154:157], v[98:101], v[162:165], v[154:157]
	v_mfma_f32_16x16x32_bf16 v[142:145], v[134:137], v[162:165], v[142:145]
	v_mfma_f32_16x16x32_bf16 v[130:133], v[98:101], v[170:173], v[130:133]
	v_mfma_f32_16x16x32_bf16 v[122:125], v[134:137], v[170:173], v[122:125]
	v_mfma_f32_16x16x32_bf16 v[110:113], v[98:101], v[178:181], v[110:113]
	v_mfma_f32_16x16x32_bf16 v[102:105], v[134:137], v[178:181], v[102:105]
	v_mfma_f32_16x16x32_bf16 v[72:75], v[98:101], v[224:227], v[72:75]
	v_mfma_f32_16x16x32_bf16 v[64:67], v[134:137], v[224:227], v[64:67]
	v_mfma_f32_16x16x32_bf16 v[154:157], v[114:117], v[166:169], v[154:157]
	v_mfma_f32_16x16x32_bf16 v[142:145], v[150:153], v[166:169], v[142:145]
	v_mfma_f32_16x16x32_bf16 v[130:133], v[114:117], v[174:177], v[130:133]
	v_mfma_f32_16x16x32_bf16 v[122:125], v[150:153], v[174:177], v[122:125]
	v_mfma_f32_16x16x32_bf16 v[110:113], v[114:117], v[220:223], v[110:113]
	v_mfma_f32_16x16x32_bf16 v[102:105], v[150:153], v[220:223], v[102:105]
	v_mfma_f32_16x16x32_bf16 v[72:75], v[114:117], v[228:231], v[72:75]
	v_mfma_f32_16x16x32_bf16 v[64:67], v[150:153], v[228:231], v[64:67]
	s_barrier
	s_setprio 0
	s_add_i32 s82, s82, s31
	v_lshl_add_u64 v[232:233], s[66:67], 0, v[200:201]
	s_mov_b32 m0, s82
	ds_read_b128 v[162:165], v218 offset:16384
	ds_read_b128 v[166:169], v218 offset:17408
	ds_read_b128 v[170:173], v218 offset:18432
	ds_read_b128 v[174:177], v218 offset:19456
	ds_read_b128 v[178:181], v218 offset:20480
	ds_read_b128 v[220:223], v218 offset:21504
	ds_read_b128 v[224:227], v218 offset:22528
	ds_read_b128 v[228:231], v218 offset:23552
	global_load_lds_dwordx4 v[232:233], off
	s_add_i32 m0, s82, 0x2000
	s_add_u32 s82, s66, 0x8000
	v_lshl_add_u64 v[234:235], s[66:67], 0, v[204:205]
	s_addc_u32 s83, s67, 0
	s_add_i32 s91, s91, s31
	global_load_lds_dwordx4 v[234:235], off
	v_lshl_add_u64 v[236:237], s[82:83], 0, v[200:201]
	s_mov_b32 m0, s91
	v_lshl_add_u64 v[238:239], s[68:69], 0, v[202:203]
	global_load_lds_dwordx4 v[236:237], off
	v_lshl_add_u64 v[236:237], s[82:83], 0, v[204:205]
	s_add_i32 m0, s91, 0x2000
	s_nop 0
	global_load_lds_dwordx4 v[236:237], off
	v_lshl_add_u64 v[236:237], s[68:69], 0, v[198:199]
	s_mov_b32 m0, s72
	s_nop 0
	global_load_lds_dwordx4 v[236:237], off
	s_mov_b32 m0, s73
	s_nop 0
	global_load_lds_dwordx4 v[238:239], off
	s_waitcnt vmcnt(8)
	s_waitcnt lgkmcnt(0)
	s_setprio 1
	s_barrier
; #define PG8_STAGE(bufoff, gbase, voff) do { _Pragma("unroll") for (int _i = 0; _i < 2; ++_i) \
;         __builtin_amdgcn_global_load_lds((const unsigned*)((const char*)(gbase) + (voff)[_i]), (LAS unsigned*)(lds + (bufoff) + ldsw + _i * 8192), 16, 0, 0); } while (0)
; #define PG8_LDA(dst, b, h) do { _Pragma("unroll") for (int m = 0; m < 4; ++m) _Pragma("unroll") for (int k = 0; k < 2; ++k) dst[m][k] = *(const LAS bf16x8*)(lds + PG8_SA(b, h) + aoff + m * 2048 + k * 1024); } while (0)
; #define PG8_LDB(dst, b, h) do { _Pragma("unroll") for (int n = 0; n < 2; ++n) _Pragma("unroll") for (int k = 0; k < 2; ++k) dst[n][k] = *(const LAS bf16x8*)(lds + PG8_SB(b, h) + boff + n * 2048 + k * 1024); } while (0)
; #define PG8_MMA(ai, bj, At, Bt) do { __builtin_amdgcn_s_setprio(1); _Pragma("unroll") for (int m = 0; m < 4; ++m) _Pragma("unroll") for (int n = 0; n < 2; ++n) _Pragma("unroll") for (int k = 0; k < 2; ++k) \
;         acc[ai][bj][m][n] = MFMA16(Bt[n][k], At[m][k], acc[ai][bj][m][n]); __builtin_amdgcn_s_setprio(0); } while (0)
; #define PG8_WAIT_V(n) asm volatile("s_waitcnt vmcnt(" #n ")" ::: "memory")
; #define PG8_WAIT_L(n) asm volatile("s_waitcnt lgkmcnt(" #n ")" ::: "memory")
; #define PG8_BAR __builtin_amdgcn_s_barrier()
; #define PG8_SCHED __builtin_amdgcn_sched_barrier(0)
; template <class Epi>
; __device__ __forceinline__ void gemm_phase(LAS unsigned char* lds, const Gemm g, const StaticOrder& S, const Epi& E, int tid_) {
;     ...
;             PG8_WAIT_V(8); PG8_WAIT_L(0); PG8_BAR; PG8_MMA(1, 0, At, B0); PG8_MMA(1, 1, At, B1); PG8_BAR; PG8_SCHED;
;             PG8_LDB(B0, 1, 0); PG8_LDB(B1, 1, 1); PG8_SCHED; PG8_LDA(At, 1, 0); PG8_STAGE(PG8_SA(0, 1), a2 + hsA, voffA);
;             PG8_WAIT_V(8); PG8_WAIT_L(0); PG8_BAR; PG8_MMA(0, 0, At, B0); PG8_MMA(0, 1, At, B1); PG8_BAR; PG8_SCHED;
	v_mfma_f32_16x16x32_bf16 v[60:63], v[76:79], v[162:165], v[60:63]
	v_mfma_f32_16x16x32_bf16 v[52:55], v[90:93], v[162:165], v[52:55]
	v_mfma_f32_16x16x32_bf16 v[44:47], v[76:79], v[170:173], v[44:47]
	v_mfma_f32_16x16x32_bf16 v[36:39], v[90:93], v[170:173], v[36:39]
	v_mfma_f32_16x16x32_bf16 v[28:31], v[76:79], v[178:181], v[28:31]
	v_mfma_f32_16x16x32_bf16 v[20:23], v[90:93], v[178:181], v[20:23]
	v_mfma_f32_16x16x32_bf16 v[12:15], v[76:79], v[224:227], v[12:15]
	v_mfma_f32_16x16x32_bf16 v[4:7], v[90:93], v[224:227], v[4:7]
	v_mfma_f32_16x16x32_bf16 v[60:63], v[82:85], v[166:169], v[60:63]
	v_mfma_f32_16x16x32_bf16 v[52:55], v[94:97], v[166:169], v[52:55]
	v_mfma_f32_16x16x32_bf16 v[44:47], v[82:85], v[174:177], v[44:47]
	v_mfma_f32_16x16x32_bf16 v[36:39], v[94:97], v[174:177], v[36:39]
	v_mfma_f32_16x16x32_bf16 v[28:31], v[82:85], v[220:223], v[28:31]
	v_mfma_f32_16x16x32_bf16 v[20:23], v[94:97], v[220:223], v[20:23]
	v_mfma_f32_16x16x32_bf16 v[12:15], v[82:85], v[228:231], v[12:15]
	v_mfma_f32_16x16x32_bf16 v[4:7], v[94:97], v[228:231], v[4:7]
	v_mfma_f32_16x16x32_bf16 v[56:59], v[98:101], v[162:165], v[56:59]
	v_mfma_f32_16x16x32_bf16 v[48:51], v[134:137], v[162:165], v[48:51]
	v_mfma_f32_16x16x32_bf16 v[40:43], v[98:101], v[170:173], v[40:43]
	v_mfma_f32_16x16x32_bf16 v[32:35], v[134:137], v[170:173], v[32:35]
	v_mfma_f32_16x16x32_bf16 v[24:27], v[98:101], v[178:181], v[24:27]
	v_mfma_f32_16x16x32_bf16 v[16:19], v[134:137], v[178:181], v[16:19]
	v_mfma_f32_16x16x32_bf16 v[8:11], v[98:101], v[224:227], v[8:11]
	v_mfma_f32_16x16x32_bf16 v[0:3], v[134:137], v[224:227], v[0:3]
	v_mfma_f32_16x16x32_bf16 v[56:59], v[114:117], v[166:169], v[56:59]
	v_mfma_f32_16x16x32_bf16 v[48:51], v[150:153], v[166:169], v[48:51]
	v_mfma_f32_16x16x32_bf16 v[40:43], v[114:117], v[174:177], v[40:43]
	v_mfma_f32_16x16x32_bf16 v[32:35], v[150:153], v[174:177], v[32:35]
	v_mfma_f32_16x16x32_bf16 v[24:27], v[114:117], v[220:223], v[24:27]
	v_mfma_f32_16x16x32_bf16 v[16:19], v[150:153], v[220:223], v[16:19]
	v_mfma_f32_16x16x32_bf16 v[8:11], v[114:117], v[228:231], v[8:11]
	v_mfma_f32_16x16x32_bf16 v[0:3], v[150:153], v[228:231], v[0:3]
	s_barrier
	s_setprio 0
	s_add_i32 s82, 0, 0x18000
	s_add_i32 s83, 0, 0x1c000
	v_add_u32_e32 v94, s82, v81
	v_add_u32_e32 v150, s83, v81
	ds_read_b128 v[76:79], v94
	ds_read_b128 v[82:85], v94 offset:1024
	ds_read_b128 v[90:93], v94 offset:2048
	ds_read_b128 v[94:97], v94 offset:3072
	ds_read_b128 v[98:101], v150
	ds_read_b128 v[114:117], v150 offset:1024
	ds_read_b128 v[134:137], v150 offset:2048
	ds_read_b128 v[150:153], v150 offset:3072
	s_add_u32 s68, s68, 0x40000
	s_addc_u32 s69, s69, 0
	s_mov_b32 m0, s74
	v_lshl_add_u64 v[240:241], s[68:69], 0, v[198:199]
	ds_read_b128 v[162:165], v218 offset:32768
	ds_read_b128 v[166:169], v218 offset:33792
	ds_read_b128 v[170:173], v218 offset:34816
	ds_read_b128 v[174:177], v218 offset:35840
	ds_read_b128 v[178:181], v218 offset:36864
	ds_read_b128 v[220:223], v218 offset:37888
	ds_read_b128 v[224:227], v218 offset:38912
	ds_read_b128 v[228:231], v218 offset:39936
	global_load_lds_dwordx4 v[240:241], off
	v_lshl_add_u64 v[240:241], s[68:69], 0, v[202:203]
	s_mov_b32 m0, s75
	s_nop 0
	global_load_lds_dwordx4 v[240:241], off
	s_waitcnt vmcnt(8)
	s_waitcnt lgkmcnt(0)
	s_setprio 1
	s_barrier
	v_mfma_f32_16x16x32_bf16 v[158:161], v[76:79], v[162:165], v[158:161]
	v_mfma_f32_16x16x32_bf16 v[146:149], v[90:93], v[162:165], v[146:149]
	v_mfma_f32_16x16x32_bf16 v[138:141], v[76:79], v[170:173], v[138:141]
	v_mfma_f32_16x16x32_bf16 v[126:129], v[90:93], v[170:173], v[126:129]
	v_mfma_f32_16x16x32_bf16 v[118:121], v[76:79], v[178:181], v[118:121]
	v_mfma_f32_16x16x32_bf16 v[106:109], v[90:93], v[178:181], v[106:109]
	v_mfma_f32_16x16x32_bf16 v[86:89], v[76:79], v[224:227], v[86:89]
	v_mfma_f32_16x16x32_bf16 v[68:71], v[90:93], v[224:227], v[68:71]
	v_mfma_f32_16x16x32_bf16 v[158:161], v[82:85], v[166:169], v[158:161]
	v_mfma_f32_16x16x32_bf16 v[146:149], v[94:97], v[166:169], v[146:149]
	v_mfma_f32_16x16x32_bf16 v[138:141], v[82:85], v[174:177], v[138:141]
	v_mfma_f32_16x16x32_bf16 v[126:129], v[94:97], v[174:177], v[126:129]
	v_mfma_f32_16x16x32_bf16 v[118:121], v[82:85], v[220:223], v[118:121]
	v_mfma_f32_16x16x32_bf16 v[106:109], v[94:97], v[220:223], v[106:109]
	v_mfma_f32_16x16x32_bf16 v[86:89], v[82:85], v[228:231], v[86:89]
	v_mfma_f32_16x16x32_bf16 v[68:71], v[94:97], v[228:231], v[68:71]
	v_mfma_f32_16x16x32_bf16 v[154:157], v[98:101], v[162:165], v[154:157]
	v_mfma_f32_16x16x32_bf16 v[142:145], v[134:137], v[162:165], v[142:145]
	v_mfma_f32_16x16x32_bf16 v[130:133], v[98:101], v[170:173], v[130:133]
	v_mfma_f32_16x16x32_bf16 v[122:125], v[134:137], v[170:173], v[122:125]
	v_mfma_f32_16x16x32_bf16 v[110:113], v[98:101], v[178:181], v[110:113]
	v_mfma_f32_16x16x32_bf16 v[102:105], v[134:137], v[178:181], v[102:105]
	v_mfma_f32_16x16x32_bf16 v[72:75], v[98:101], v[224:227], v[72:75]
	v_mfma_f32_16x16x32_bf16 v[64:67], v[134:137], v[224:227], v[64:67]
	v_mfma_f32_16x16x32_bf16 v[154:157], v[114:117], v[166:169], v[154:157]
	v_mfma_f32_16x16x32_bf16 v[142:145], v[150:153], v[166:169], v[142:145]
	v_mfma_f32_16x16x32_bf16 v[130:133], v[114:117], v[174:177], v[130:133]
	v_mfma_f32_16x16x32_bf16 v[122:125], v[150:153], v[174:177], v[122:125]
	v_mfma_f32_16x16x32_bf16 v[110:113], v[114:117], v[220:223], v[110:113]
	v_mfma_f32_16x16x32_bf16 v[102:105], v[150:153], v[220:223], v[102:105]
	v_mfma_f32_16x16x32_bf16 v[72:75], v[114:117], v[228:231], v[72:75]
	v_mfma_f32_16x16x32_bf16 v[64:67], v[150:153], v[228:231], v[64:67]
	s_barrier
; #define PG8_STAGE(bufoff, gbase, voff) do { _Pragma("unroll") for (int _i = 0; _i < 2; ++_i) \
;         __builtin_amdgcn_global_load_lds((const unsigned*)((const char*)(gbase) + (voff)[_i]), (LAS unsigned*)(lds + (bufoff) + ldsw + _i * 8192), 16, 0, 0); } while (0)
; #define PG8_LDA(dst, b, h) do { _Pragma("unroll") for (int m = 0; m < 4; ++m) _Pragma("unroll") for (int k = 0; k < 2; ++k) dst[m][k] = *(const LAS bf16x8*)(lds + PG8_SA(b, h) + aoff + m * 2048 + k * 1024); } while (0)
; #define PG8_MMA(ai, bj, At, Bt) do { __builtin_amdgcn_s_setprio(1); _Pragma("unroll") for (int m = 0; m < 4; ++m) _Pragma("unroll") for (int n = 0; n < 2; ++n) _Pragma("unroll") for (int k = 0; k < 2; ++k) \
;         acc[ai][bj][m][n] = MFMA16(Bt[n][k], At[m][k], acc[ai][bj][m][n]); __builtin_amdgcn_s_setprio(0); } while (0)
; #define PG8_WAIT_V(n) asm volatile("s_waitcnt vmcnt(" #n ")" ::: "memory")
; #define PG8_WAIT_L(n) asm volatile("s_waitcnt lgkmcnt(" #n ")" ::: "memory")
; #define PG8_BAR __builtin_amdgcn_s_barrier()
; #define PG8_SCHED __builtin_amdgcn_sched_barrier(0)
; template <class Epi>
; __device__ __forceinline__ void gemm_phase(LAS unsigned char* lds, const Gemm g, const StaticOrder& S, const Epi& E, int tid_) {
;     ...
;             PG8_LDA(At, 1, 1); PG8_STAGE(PG8_SB(1, 0), b3, voffB); PG8_STAGE(PG8_SB(1, 1), b3 + hsB, voffB); PG8_STAGE(PG8_SA(1, 0), a3, voffA);
;             PG8_WAIT_V(8); PG8_WAIT_L(0); PG8_BAR; PG8_MMA(1, 0, At, B0); PG8_MMA(1, 1, At, B1); PG8_BAR; PG8_SCHED;
;         }
	s_setprio 0
	s_add_i32 s68, s82, s31
	v_lshl_add_u64 v[232:233], v[232:233], 0, s[6:7]
	s_mov_b32 m0, s68
	ds_read_b128 v[162:165], v218 offset:49152
	ds_read_b128 v[166:169], v218 offset:50176
	ds_read_b128 v[170:173], v218 offset:51200
	ds_read_b128 v[174:177], v218 offset:52224
	ds_read_b128 v[178:181], v218 offset:53248
	ds_read_b128 v[220:223], v218 offset:54272
	ds_read_b128 v[224:227], v218 offset:55296
	ds_read_b128 v[228:231], v218 offset:56320
	global_load_lds_dwordx4 v[232:233], off
	s_add_i32 m0, s68, 0x2000
	s_add_u32 s66, s66, 0x8080
	v_lshl_add_u64 v[232:233], v[234:235], 0, s[6:7]
	s_addc_u32 s67, s67, 0
	s_add_i32 s68, s83, s31
	global_load_lds_dwordx4 v[232:233], off
	v_lshl_add_u64 v[232:233], s[66:67], 0, v[200:201]
	s_mov_b32 m0, s68
	s_nop 0
	global_load_lds_dwordx4 v[232:233], off
	v_lshl_add_u64 v[232:233], s[66:67], 0, v[204:205]
	s_add_i32 m0, s68, 0x2000
	s_nop 0
	global_load_lds_dwordx4 v[232:233], off
	v_lshl_add_u64 v[232:233], v[236:237], 0, s[6:7]
	s_mov_b32 m0, s4
	s_nop 0
	global_load_lds_dwordx4 v[232:233], off
	v_lshl_add_u64 v[232:233], v[238:239], 0, s[6:7]
	s_mov_b32 m0, s76
	s_nop 0
	global_load_lds_dwordx4 v[232:233], off
	s_waitcnt vmcnt(8)
	s_waitcnt lgkmcnt(0)
	s_setprio 1
	s_barrier
	v_mfma_f32_16x16x32_bf16 v[60:63], v[76:79], v[162:165], v[60:63]
	v_mfma_f32_16x16x32_bf16 v[52:55], v[90:93], v[162:165], v[52:55]
	v_mfma_f32_16x16x32_bf16 v[44:47], v[76:79], v[170:173], v[44:47]
	v_mfma_f32_16x16x32_bf16 v[36:39], v[90:93], v[170:173], v[36:39]
	v_mfma_f32_16x16x32_bf16 v[28:31], v[76:79], v[178:181], v[28:31]
	v_mfma_f32_16x16x32_bf16 v[20:23], v[90:93], v[178:181], v[20:23]
	v_mfma_f32_16x16x32_bf16 v[12:15], v[76:79], v[224:227], v[12:15]
	v_mfma_f32_16x16x32_bf16 v[4:7], v[90:93], v[224:227], v[4:7]
	v_mfma_f32_16x16x32_bf16 v[60:63], v[82:85], v[166:169], v[60:63]
	v_mfma_f32_16x16x32_bf16 v[52:55], v[94:97], v[166:169], v[52:55]
	v_mfma_f32_16x16x32_bf16 v[44:47], v[82:85], v[174:177], v[44:47]
	v_mfma_f32_16x16x32_bf16 v[36:39], v[94:97], v[174:177], v[36:39]
	v_mfma_f32_16x16x32_bf16 v[28:31], v[82:85], v[220:223], v[28:31]
	v_mfma_f32_16x16x32_bf16 v[20:23], v[94:97], v[220:223], v[20:23]
	v_mfma_f32_16x16x32_bf16 v[12:15], v[82:85], v[228:231], v[12:15]
	v_mfma_f32_16x16x32_bf16 v[4:7], v[94:97], v[228:231], v[4:7]
	v_mfma_f32_16x16x32_bf16 v[56:59], v[98:101], v[162:165], v[56:59]
	v_mfma_f32_16x16x32_bf16 v[48:51], v[134:137], v[162:165], v[48:51]
	v_mfma_f32_16x16x32_bf16 v[40:43], v[98:101], v[170:173], v[40:43]
	v_mfma_f32_16x16x32_bf16 v[32:35], v[134:137], v[170:173], v[32:35]
	v_mfma_f32_16x16x32_bf16 v[24:27], v[98:101], v[178:181], v[24:27]
	v_mfma_f32_16x16x32_bf16 v[16:19], v[134:137], v[178:181], v[16:19]
	v_mfma_f32_16x16x32_bf16 v[8:11], v[98:101], v[224:227], v[8:11]
	v_mfma_f32_16x16x32_bf16 v[0:3], v[134:137], v[224:227], v[0:3]
	v_mfma_f32_16x16x32_bf16 v[56:59], v[114:117], v[166:169], v[56:59]
	v_mfma_f32_16x16x32_bf16 v[48:51], v[150:153], v[166:169], v[48:51]
	v_mfma_f32_16x16x32_bf16 v[40:43], v[114:117], v[174:177], v[40:43]
	v_mfma_f32_16x16x32_bf16 v[32:35], v[150:153], v[174:177], v[32:35]
	v_mfma_f32_16x16x32_bf16 v[24:27], v[114:117], v[220:223], v[24:27]
	v_mfma_f32_16x16x32_bf16 v[16:19], v[150:153], v[220:223], v[16:19]
	v_mfma_f32_16x16x32_bf16 v[8:11], v[114:117], v[228:231], v[8:11]
	v_mfma_f32_16x16x32_bf16 v[0:3], v[150:153], v[228:231], v[0:3]
	s_barrier
	s_setprio 0
	s_add_u32 s64, s64, 0x100
	s_addc_u32 s65, s65, 0
	s_add_u32 s59, s59, 0x100
	s_addc_u32 s80, s80, 0
	s_cmp_ge_i32 s81, s18
	s_mov_b32 s66, s81
	s_cbranch_scc0 .LBB0_320
	s_and_b64 vcc, exec, s[54:55]
	s_cbranch_vccz .LBB0_323

; #define PG8_STAGE(bufoff, gbase, voff) do { _Pragma("unroll") for (int _i = 0; _i < 2; ++_i) \
;         __builtin_amdgcn_global_load_lds((const unsigned*)((const char*)(gbase) + (voff)[_i]), (LAS unsigned*)(lds + (bufoff) + ldsw + _i * 8192), 16, 0, 0); } while (0)
; #define PG8_LDA(dst, b, h) do { _Pragma("unroll") for (int m = 0; m < 4; ++m) _Pragma("unroll") for (int k = 0; k < 2; ++k) dst[m][k] = *(const LAS bf16x8*)(lds + PG8_SA(b, h) + aoff + m * 2048 + k * 1024); } while (0)
; #define PG8_LDB(dst, b, h) do { _Pragma("unroll") for (int n = 0; n < 2; ++n) _Pragma("unroll") for (int k = 0; k < 2; ++k) dst[n][k] = *(const LAS bf16x8*)(lds + PG8_SB(b, h) + boff + n * 2048 + k * 1024); } while (0)
; #define PG8_MMA(ai, bj, At, Bt) do { __builtin_amdgcn_s_setprio(1); _Pragma("unroll") for (int m = 0; m < 4; ++m) _Pragma("unroll") for (int n = 0; n < 2; ++n) _Pragma("unroll") for (int k = 0; k < 2; ++k) \
;         acc[ai][bj][m][n] = MFMA16(Bt[n][k], At[m][k], acc[ai][bj][m][n]); __builtin_amdgcn_s_setprio(0); } while (0)
; #define PG8_WAIT_V(n) asm volatile("s_waitcnt vmcnt(" #n ")" ::: "memory")
; #define PG8_WAIT_L(n) asm volatile("s_waitcnt lgkmcnt(" #n ")" ::: "memory")
; #define PG8_BAR __builtin_amdgcn_s_barrier()
; #define PG8_SCHED __builtin_amdgcn_sched_barrier(0)
; template <class Epi>
; __device__ __forceinline__ void gemm_phase(LAS unsigned char* lds, const Gemm g, const StaticOrder& S, const Epi& E, int tid_) {
;     ...
;             const bool last = (t == nt - 2);
;             const char* a1 = cA + (size_t)(t + 1) * kstep;
;             const char* a2 = last ? nA : cA + (size_t)(t + 2) * kstep; const char* b2 = last ? nB : cB + (size_t)(t + 2) * kstep;
;             const char* a3 = a2 + kstep; const char* b3 = b2 + kstep;
;             PG8_LDB(B0, 0, 0); PG8_LDB(B1, 0, 1); PG8_SCHED; PG8_LDA(At, 0, 0); PG8_STAGE(PG8_SA(1, 1), a1 + hsA, voffA);
;             PG8_WAIT_V(8); PG8_WAIT_L(0); PG8_BAR; PG8_MMA(0, 0, At, B0); PG8_MMA(0, 1, At, B1); PG8_BAR; PG8_SCHED;
;             PG8_LDA(At, 0, 1); PG8_STAGE(PG8_SB(0, 0), b2, voffB); PG8_STAGE(PG8_SB(0, 1), b2 + hsB, voffB); PG8_STAGE(PG8_SA(0, 0), a2, voffA);
.LBB0_455:
	s_add_i32 s74, s40, 2
	s_add_u32 s41, s28, 0xfffc0080
	s_addc_u32 s60, s29, -1
	s_add_i32 s75, 0, 0x10000
	s_cmp_eq_u32 s68, s40
	s_cselect_b32 s61, s22, s60
	s_cselect_b32 s60, s23, s41
	s_cselect_b32 s41, s25, s73
	s_cselect_b32 s40, s51, s72
	s_add_i32 s78, 0, 0x14000
	v_add_u32_e32 v142, s75, v165
	v_add_u32_e32 v162, s78, v165
	ds_read_b128 v[130:133], v142
	s_waitcnt lgkmcnt(0)
	ds_read_b128 v[134:137], v142 offset:1024
	ds_read_b128 v[138:141], v142 offset:2048
	ds_read_b128 v[142:145], v142 offset:3072
	ds_read_b128 v[158:161], v162
	ds_read_b128 v[174:177], v162 offset:1024
	ds_read_b128 v[178:181], v162 offset:2048
	ds_read_b128 v[198:201], v162 offset:3072
	v_lshl_add_u64 v[162:163], s[28:29], 0, v[154:155]
	s_add_i32 m0, s62, 0xc000
	ds_read_b128 v[202:205], v173
	ds_read_b128 v[206:209], v173 offset:1024
	ds_read_b128 v[216:219], v173 offset:2048
	ds_read_b128 v[220:223], v173 offset:3072
	ds_read_b128 v[224:227], v173 offset:4096
	ds_read_b128 v[228:231], v173 offset:5120
	ds_read_b128 v[232:235], v173 offset:6144
	ds_read_b128 v[236:239], v173 offset:7168
	global_load_lds_dwordx4 v[162:163], off
	v_lshl_add_u64 v[162:163], s[28:29], 0, v[156:157]
	s_add_i32 m0, s62, 0xe000
	s_nop 0
	global_load_lds_dwordx4 v[162:163], off
	s_waitcnt vmcnt(8)
	s_waitcnt lgkmcnt(0)
	s_setprio 1
	s_barrier
	v_mfma_f32_16x16x32_bf16 v[126:129], v[130:133], v[202:205], v[126:129]
	v_mfma_f32_16x16x32_bf16 v[122:125], v[138:141], v[202:205], v[122:125]
	v_mfma_f32_16x16x32_bf16 v[110:113], v[130:133], v[216:219], v[110:113]
	v_mfma_f32_16x16x32_bf16 v[106:109], v[138:141], v[216:219], v[106:109]
	v_mfma_f32_16x16x32_bf16 v[94:97], v[130:133], v[224:227], v[94:97]
	v_mfma_f32_16x16x32_bf16 v[90:93], v[138:141], v[224:227], v[90:93]
	v_mfma_f32_16x16x32_bf16 v[76:79], v[130:133], v[232:235], v[76:79]
	v_mfma_f32_16x16x32_bf16 v[72:75], v[138:141], v[232:235], v[72:75]
	v_mfma_f32_16x16x32_bf16 v[126:129], v[134:137], v[206:209], v[126:129]
	v_mfma_f32_16x16x32_bf16 v[122:125], v[142:145], v[206:209], v[122:125]
	v_mfma_f32_16x16x32_bf16 v[110:113], v[134:137], v[220:223], v[110:113]
	v_mfma_f32_16x16x32_bf16 v[106:109], v[142:145], v[220:223], v[106:109]
	v_mfma_f32_16x16x32_bf16 v[94:97], v[134:137], v[228:231], v[94:97]
	v_mfma_f32_16x16x32_bf16 v[90:93], v[142:145], v[228:231], v[90:93]
	v_mfma_f32_16x16x32_bf16 v[76:79], v[134:137], v[236:239], v[76:79]
	v_mfma_f32_16x16x32_bf16 v[72:75], v[142:145], v[236:239], v[72:75]
	v_mfma_f32_16x16x32_bf16 v[118:121], v[158:161], v[202:205], v[118:121]
	v_mfma_f32_16x16x32_bf16 v[114:117], v[178:181], v[202:205], v[114:117]
	v_mfma_f32_16x16x32_bf16 v[102:105], v[158:161], v[216:219], v[102:105]
	v_mfma_f32_16x16x32_bf16 v[98:101], v[178:181], v[216:219], v[98:101]
	v_mfma_f32_16x16x32_bf16 v[86:89], v[158:161], v[224:227], v[86:89]
	v_mfma_f32_16x16x32_bf16 v[82:85], v[178:181], v[224:227], v[82:85]
	v_mfma_f32_16x16x32_bf16 v[68:71], v[158:161], v[232:235], v[68:71]
	v_mfma_f32_16x16x32_bf16 v[64:67], v[178:181], v[232:235], v[64:67]
	v_mfma_f32_16x16x32_bf16 v[118:121], v[174:177], v[206:209], v[118:121]
	v_mfma_f32_16x16x32_bf16 v[114:117], v[198:201], v[206:209], v[114:117]
	v_mfma_f32_16x16x32_bf16 v[102:105], v[174:177], v[220:223], v[102:105]
	v_mfma_f32_16x16x32_bf16 v[98:101], v[198:201], v[220:223], v[98:101]
	v_mfma_f32_16x16x32_bf16 v[86:89], v[174:177], v[228:231], v[86:89]
	v_mfma_f32_16x16x32_bf16 v[82:85], v[198:201], v[228:231], v[82:85]
	v_mfma_f32_16x16x32_bf16 v[68:71], v[174:177], v[236:239], v[68:71]
	v_mfma_f32_16x16x32_bf16 v[64:67], v[198:201], v[236:239], v[64:67]
	s_barrier
	s_setprio 0
	s_add_i32 s75, s75, s31
	v_lshl_add_u64 v[162:163], s[40:41], 0, v[150:151]
	s_mov_b32 m0, s75
	ds_read_b128 v[202:205], v173 offset:16384
	ds_read_b128 v[206:209], v173 offset:17408
	ds_read_b128 v[216:219], v173 offset:18432
	ds_read_b128 v[220:223], v173 offset:19456
	ds_read_b128 v[224:227], v173 offset:20480
	ds_read_b128 v[228:231], v173 offset:21504
	ds_read_b128 v[232:235], v173 offset:22528
	ds_read_b128 v[236:239], v173 offset:23552
	global_load_lds_dwordx4 v[162:163], off
	s_add_i32 m0, s75, 0x2000
	s_add_u32 s76, s40, 0x40000
	v_lshl_add_u64 v[240:241], s[40:41], 0, v[146:147]
	s_addc_u32 s77, s41, 0
	s_add_i32 s75, s78, s31
	global_load_lds_dwordx4 v[240:241], off
	v_lshl_add_u64 v[242:243], s[76:77], 0, v[150:151]
	s_mov_b32 m0, s75
	v_lshl_add_u64 v[244:245], s[60:61], 0, v[148:149]
	global_load_lds_dwordx4 v[242:243], off
	v_lshl_add_u64 v[242:243], s[76:77], 0, v[146:147]
	s_add_i32 m0, s75, 0x2000
	s_nop 0
	global_load_lds_dwordx4 v[242:243], off
	v_lshl_add_u64 v[242:243], s[60:61], 0, v[152:153]
	s_mov_b32 m0, s62
	s_nop 0
	global_load_lds_dwordx4 v[242:243], off
	s_mov_b32 m0, s63
	s_nop 0
	global_load_lds_dwordx4 v[244:245], off
	s_waitcnt vmcnt(8)
	s_waitcnt lgkmcnt(0)
	s_setprio 1
	s_barrier
; #define PG8_STAGE(bufoff, gbase, voff) do { _Pragma("unroll") for (int _i = 0; _i < 2; ++_i) \
;         __builtin_amdgcn_global_load_lds((const unsigned*)((const char*)(gbase) + (voff)[_i]), (LAS unsigned*)(lds + (bufoff) + ldsw + _i * 8192), 16, 0, 0); } while (0)
; #define PG8_LDA(dst, b, h) do { _Pragma("unroll") for (int m = 0; m < 4; ++m) _Pragma("unroll") for (int k = 0; k < 2; ++k) dst[m][k] = *(const LAS bf16x8*)(lds + PG8_SA(b, h) + aoff + m * 2048 + k * 1024); } while (0)
; #define PG8_LDB(dst, b, h) do { _Pragma("unroll") for (int n = 0; n < 2; ++n) _Pragma("unroll") for (int k = 0; k < 2; ++k) dst[n][k] = *(const LAS bf16x8*)(lds + PG8_SB(b, h) + boff + n * 2048 + k * 1024); } while (0)
; #define PG8_MMA(ai, bj, At, Bt) do { __builtin_amdgcn_s_setprio(1); _Pragma("unroll") for (int m = 0; m < 4; ++m) _Pragma("unroll") for (int n = 0; n < 2; ++n) _Pragma("unroll") for (int k = 0; k < 2; ++k) \
;         acc[ai][bj][m][n] = MFMA16(Bt[n][k], At[m][k], acc[ai][bj][m][n]); __builtin_amdgcn_s_setprio(0); } while (0)
; #define PG8_WAIT_V(n) asm volatile("s_waitcnt vmcnt(" #n ")" ::: "memory")
; #define PG8_WAIT_L(n) asm volatile("s_waitcnt lgkmcnt(" #n ")" ::: "memory")
; #define PG8_BAR __builtin_amdgcn_s_barrier()
; #define PG8_SCHED __builtin_amdgcn_sched_barrier(0)
; template <class Epi>
; __device__ __forceinline__ void gemm_phase(LAS unsigned char* lds, const Gemm g, const StaticOrder& S, const Epi& E, int tid_) {
;     ...
;             PG8_WAIT_V(8); PG8_WAIT_L(0); PG8_BAR; PG8_MMA(1, 0, At, B0); PG8_MMA(1, 1, At, B1); PG8_BAR; PG8_SCHED;
;             PG8_LDB(B0, 1, 0); PG8_LDB(B1, 1, 1); PG8_SCHED; PG8_LDA(At, 1, 0); PG8_STAGE(PG8_SA(0, 1), a2 + hsA, voffA);
;             PG8_WAIT_V(8); PG8_WAIT_L(0); PG8_BAR; PG8_MMA(0, 0, At, B0); PG8_MMA(0, 1, At, B1); PG8_BAR; PG8_SCHED;
	v_mfma_f32_16x16x32_bf16 v[60:63], v[130:133], v[202:205], v[60:63]
	v_mfma_f32_16x16x32_bf16 v[56:59], v[138:141], v[202:205], v[56:59]
	v_mfma_f32_16x16x32_bf16 v[44:47], v[130:133], v[216:219], v[44:47]
	v_mfma_f32_16x16x32_bf16 v[40:43], v[138:141], v[216:219], v[40:43]
	v_mfma_f32_16x16x32_bf16 v[28:31], v[130:133], v[224:227], v[28:31]
	v_mfma_f32_16x16x32_bf16 v[24:27], v[138:141], v[224:227], v[24:27]
	v_mfma_f32_16x16x32_bf16 v[12:15], v[130:133], v[232:235], v[12:15]
	v_mfma_f32_16x16x32_bf16 v[8:11], v[138:141], v[232:235], v[8:11]
	v_mfma_f32_16x16x32_bf16 v[60:63], v[134:137], v[206:209], v[60:63]
	v_mfma_f32_16x16x32_bf16 v[56:59], v[142:145], v[206:209], v[56:59]
	v_mfma_f32_16x16x32_bf16 v[44:47], v[134:137], v[220:223], v[44:47]
	v_mfma_f32_16x16x32_bf16 v[40:43], v[142:145], v[220:223], v[40:43]
	v_mfma_f32_16x16x32_bf16 v[28:31], v[134:137], v[228:231], v[28:31]
	v_mfma_f32_16x16x32_bf16 v[24:27], v[142:145], v[228:231], v[24:27]
	v_mfma_f32_16x16x32_bf16 v[12:15], v[134:137], v[236:239], v[12:15]
	v_mfma_f32_16x16x32_bf16 v[8:11], v[142:145], v[236:239], v[8:11]
	v_mfma_f32_16x16x32_bf16 v[52:55], v[158:161], v[202:205], v[52:55]
	v_mfma_f32_16x16x32_bf16 v[48:51], v[178:181], v[202:205], v[48:51]
	v_mfma_f32_16x16x32_bf16 v[36:39], v[158:161], v[216:219], v[36:39]
	v_mfma_f32_16x16x32_bf16 v[32:35], v[178:181], v[216:219], v[32:35]
	v_mfma_f32_16x16x32_bf16 v[20:23], v[158:161], v[224:227], v[20:23]
	v_mfma_f32_16x16x32_bf16 v[16:19], v[178:181], v[224:227], v[16:19]
	v_mfma_f32_16x16x32_bf16 v[4:7], v[158:161], v[232:235], v[4:7]
	v_mfma_f32_16x16x32_bf16 v[0:3], v[178:181], v[232:235], v[0:3]
	v_mfma_f32_16x16x32_bf16 v[52:55], v[174:177], v[206:209], v[52:55]
	v_mfma_f32_16x16x32_bf16 v[48:51], v[198:201], v[206:209], v[48:51]
	v_mfma_f32_16x16x32_bf16 v[36:39], v[174:177], v[220:223], v[36:39]
	v_mfma_f32_16x16x32_bf16 v[32:35], v[198:201], v[220:223], v[32:35]
	v_mfma_f32_16x16x32_bf16 v[20:23], v[174:177], v[228:231], v[20:23]
	v_mfma_f32_16x16x32_bf16 v[16:19], v[198:201], v[228:231], v[16:19]
	v_mfma_f32_16x16x32_bf16 v[4:7], v[174:177], v[236:239], v[4:7]
	v_mfma_f32_16x16x32_bf16 v[0:3], v[198:201], v[236:239], v[0:3]
	s_barrier
	s_setprio 0
	s_add_i32 s75, 0, 0x18000
	s_add_i32 s76, 0, 0x1c000
	v_add_u32_e32 v142, s75, v165
	v_add_u32_e32 v198, s76, v165
	ds_read_b128 v[130:133], v142
	ds_read_b128 v[134:137], v142 offset:1024
	ds_read_b128 v[138:141], v142 offset:2048
	ds_read_b128 v[142:145], v142 offset:3072
	ds_read_b128 v[158:161], v198
	ds_read_b128 v[174:177], v198 offset:1024
	ds_read_b128 v[178:181], v198 offset:2048
	ds_read_b128 v[198:201], v198 offset:3072
	s_add_u32 s60, s60, 0x40000
	s_addc_u32 s61, s61, 0
	s_mov_b32 m0, s64
	v_lshl_add_u64 v[246:247], s[60:61], 0, v[152:153]
	ds_read_b128 v[202:205], v173 offset:32768
	ds_read_b128 v[206:209], v173 offset:33792
	ds_read_b128 v[216:219], v173 offset:34816
	ds_read_b128 v[220:223], v173 offset:35840
	ds_read_b128 v[224:227], v173 offset:36864
	ds_read_b128 v[228:231], v173 offset:37888
	ds_read_b128 v[232:235], v173 offset:38912
	ds_read_b128 v[236:239], v173 offset:39936
	global_load_lds_dwordx4 v[246:247], off
	v_lshl_add_u64 v[246:247], s[60:61], 0, v[148:149]
	s_mov_b32 m0, s65
	s_nop 0
	global_load_lds_dwordx4 v[246:247], off
	s_waitcnt vmcnt(8)
	s_waitcnt lgkmcnt(0)
	s_setprio 1
	s_barrier
	v_mfma_f32_16x16x32_bf16 v[126:129], v[130:133], v[202:205], v[126:129]
	v_mfma_f32_16x16x32_bf16 v[122:125], v[138:141], v[202:205], v[122:125]
	v_mfma_f32_16x16x32_bf16 v[110:113], v[130:133], v[216:219], v[110:113]
	v_mfma_f32_16x16x32_bf16 v[106:109], v[138:141], v[216:219], v[106:109]
	v_mfma_f32_16x16x32_bf16 v[94:97], v[130:133], v[224:227], v[94:97]
	v_mfma_f32_16x16x32_bf16 v[90:93], v[138:141], v[224:227], v[90:93]
	v_mfma_f32_16x16x32_bf16 v[76:79], v[130:133], v[232:235], v[76:79]
	v_mfma_f32_16x16x32_bf16 v[72:75], v[138:141], v[232:235], v[72:75]
	v_mfma_f32_16x16x32_bf16 v[126:129], v[134:137], v[206:209], v[126:129]
	v_mfma_f32_16x16x32_bf16 v[122:125], v[142:145], v[206:209], v[122:125]
	v_mfma_f32_16x16x32_bf16 v[110:113], v[134:137], v[220:223], v[110:113]
	v_mfma_f32_16x16x32_bf16 v[106:109], v[142:145], v[220:223], v[106:109]
	v_mfma_f32_16x16x32_bf16 v[94:97], v[134:137], v[228:231], v[94:97]
	v_mfma_f32_16x16x32_bf16 v[90:93], v[142:145], v[228:231], v[90:93]
	v_mfma_f32_16x16x32_bf16 v[76:79], v[134:137], v[236:239], v[76:79]
	v_mfma_f32_16x16x32_bf16 v[72:75], v[142:145], v[236:239], v[72:75]
	v_mfma_f32_16x16x32_bf16 v[118:121], v[158:161], v[202:205], v[118:121]
	v_mfma_f32_16x16x32_bf16 v[114:117], v[178:181], v[202:205], v[114:117]
	v_mfma_f32_16x16x32_bf16 v[102:105], v[158:161], v[216:219], v[102:105]
	v_mfma_f32_16x16x32_bf16 v[98:101], v[178:181], v[216:219], v[98:101]
	v_mfma_f32_16x16x32_bf16 v[86:89], v[158:161], v[224:227], v[86:89]
	v_mfma_f32_16x16x32_bf16 v[82:85], v[178:181], v[224:227], v[82:85]
	v_mfma_f32_16x16x32_bf16 v[68:71], v[158:161], v[232:235], v[68:71]
	v_mfma_f32_16x16x32_bf16 v[64:67], v[178:181], v[232:235], v[64:67]
	v_mfma_f32_16x16x32_bf16 v[118:121], v[174:177], v[206:209], v[118:121]
	v_mfma_f32_16x16x32_bf16 v[114:117], v[198:201], v[206:209], v[114:117]
	v_mfma_f32_16x16x32_bf16 v[102:105], v[174:177], v[220:223], v[102:105]
	v_mfma_f32_16x16x32_bf16 v[98:101], v[198:201], v[220:223], v[98:101]
	v_mfma_f32_16x16x32_bf16 v[86:89], v[174:177], v[228:231], v[86:89]
	v_mfma_f32_16x16x32_bf16 v[82:85], v[198:201], v[228:231], v[82:85]
	v_mfma_f32_16x16x32_bf16 v[68:71], v[174:177], v[236:239], v[68:71]
	v_mfma_f32_16x16x32_bf16 v[64:67], v[198:201], v[236:239], v[64:67]
	s_barrier
; #define PG8_STAGE(bufoff, gbase, voff) do { _Pragma("unroll") for (int _i = 0; _i < 2; ++_i) \
;         __builtin_amdgcn_global_load_lds((const unsigned*)((const char*)(gbase) + (voff)[_i]), (LAS unsigned*)(lds + (bufoff) + ldsw + _i * 8192), 16, 0, 0); } while (0)
; #define PG8_LDA(dst, b, h) do { _Pragma("unroll") for (int m = 0; m < 4; ++m) _Pragma("unroll") for (int k = 0; k < 2; ++k) dst[m][k] = *(const LAS bf16x8*)(lds + PG8_SA(b, h) + aoff + m * 2048 + k * 1024); } while (0)
; #define PG8_MMA(ai, bj, At, Bt) do { __builtin_amdgcn_s_setprio(1); _Pragma("unroll") for (int m = 0; m < 4; ++m) _Pragma("unroll") for (int n = 0; n < 2; ++n) _Pragma("unroll") for (int k = 0; k < 2; ++k) \
;         acc[ai][bj][m][n] = MFMA16(Bt[n][k], At[m][k], acc[ai][bj][m][n]); __builtin_amdgcn_s_setprio(0); } while (0)
; #define PG8_WAIT_V(n) asm volatile("s_waitcnt vmcnt(" #n ")" ::: "memory")
; #define PG8_WAIT_L(n) asm volatile("s_waitcnt lgkmcnt(" #n ")" ::: "memory")
; #define PG8_BAR __builtin_amdgcn_s_barrier()
; #define PG8_SCHED __builtin_amdgcn_sched_barrier(0)
; template <class Epi>
; __device__ __forceinline__ void gemm_phase(LAS unsigned char* lds, const Gemm g, const StaticOrder& S, const Epi& E, int tid_) {
;     ...
;             PG8_LDA(At, 1, 1); PG8_STAGE(PG8_SB(1, 0), b3, voffB); PG8_STAGE(PG8_SB(1, 1), b3 + hsB, voffB); PG8_STAGE(PG8_SA(1, 0), a3, voffA);
;             PG8_WAIT_V(8); PG8_WAIT_L(0); PG8_BAR; PG8_MMA(1, 0, At, B0); PG8_MMA(1, 1, At, B1); PG8_BAR; PG8_SCHED;
;         }
	s_setprio 0
	s_add_i32 s60, s75, s31
	v_lshl_add_u64 v[162:163], v[162:163], 0, s[6:7]
	s_mov_b32 m0, s60
	ds_read_b128 v[202:205], v173 offset:49152
	ds_read_b128 v[206:209], v173 offset:50176
	ds_read_b128 v[216:219], v173 offset:51200
	ds_read_b128 v[220:223], v173 offset:52224
	ds_read_b128 v[224:227], v173 offset:53248
	ds_read_b128 v[228:231], v173 offset:54272
	ds_read_b128 v[232:235], v173 offset:55296
	ds_read_b128 v[236:239], v173 offset:56320
	global_load_lds_dwordx4 v[162:163], off
	s_add_i32 m0, s60, 0x2000
	s_add_u32 s40, s40, 0x40080
	v_lshl_add_u64 v[162:163], v[240:241], 0, s[6:7]
	s_addc_u32 s41, s41, 0
	s_add_i32 s60, s76, s31
	global_load_lds_dwordx4 v[162:163], off
	v_lshl_add_u64 v[162:163], s[40:41], 0, v[150:151]
	s_mov_b32 m0, s60
	s_nop 0
	global_load_lds_dwordx4 v[162:163], off
	v_lshl_add_u64 v[162:163], s[40:41], 0, v[146:147]
	s_add_i32 m0, s60, 0x2000
	s_nop 0
	global_load_lds_dwordx4 v[162:163], off
	v_lshl_add_u64 v[162:163], v[242:243], 0, s[6:7]
	s_mov_b32 m0, s4
	s_nop 0
	global_load_lds_dwordx4 v[162:163], off
	v_lshl_add_u64 v[162:163], v[244:245], 0, s[6:7]
	s_mov_b32 m0, s66
	s_nop 0
	global_load_lds_dwordx4 v[162:163], off
	s_waitcnt vmcnt(8)
	s_waitcnt lgkmcnt(0)
	s_setprio 1
	s_barrier
	v_mfma_f32_16x16x32_bf16 v[60:63], v[130:133], v[202:205], v[60:63]
	v_mfma_f32_16x16x32_bf16 v[56:59], v[138:141], v[202:205], v[56:59]
	v_mfma_f32_16x16x32_bf16 v[44:47], v[130:133], v[216:219], v[44:47]
	v_mfma_f32_16x16x32_bf16 v[40:43], v[138:141], v[216:219], v[40:43]
	v_mfma_f32_16x16x32_bf16 v[28:31], v[130:133], v[224:227], v[28:31]
	v_mfma_f32_16x16x32_bf16 v[24:27], v[138:141], v[224:227], v[24:27]
	v_mfma_f32_16x16x32_bf16 v[12:15], v[130:133], v[232:235], v[12:15]
	v_mfma_f32_16x16x32_bf16 v[8:11], v[138:141], v[232:235], v[8:11]
	v_mfma_f32_16x16x32_bf16 v[60:63], v[134:137], v[206:209], v[60:63]
	v_mfma_f32_16x16x32_bf16 v[56:59], v[142:145], v[206:209], v[56:59]
	v_mfma_f32_16x16x32_bf16 v[44:47], v[134:137], v[220:223], v[44:47]
	v_mfma_f32_16x16x32_bf16 v[40:43], v[142:145], v[220:223], v[40:43]
	v_mfma_f32_16x16x32_bf16 v[28:31], v[134:137], v[228:231], v[28:31]
	v_mfma_f32_16x16x32_bf16 v[24:27], v[142:145], v[228:231], v[24:27]
	v_mfma_f32_16x16x32_bf16 v[12:15], v[134:137], v[236:239], v[12:15]
	v_mfma_f32_16x16x32_bf16 v[8:11], v[142:145], v[236:239], v[8:11]
	v_mfma_f32_16x16x32_bf16 v[52:55], v[158:161], v[202:205], v[52:55]
	v_mfma_f32_16x16x32_bf16 v[48:51], v[178:181], v[202:205], v[48:51]
	v_mfma_f32_16x16x32_bf16 v[36:39], v[158:161], v[216:219], v[36:39]
	v_mfma_f32_16x16x32_bf16 v[32:35], v[178:181], v[216:219], v[32:35]
	v_mfma_f32_16x16x32_bf16 v[20:23], v[158:161], v[224:227], v[20:23]
	v_mfma_f32_16x16x32_bf16 v[16:19], v[178:181], v[224:227], v[16:19]
	v_mfma_f32_16x16x32_bf16 v[4:7], v[158:161], v[232:235], v[4:7]
	v_mfma_f32_16x16x32_bf16 v[0:3], v[178:181], v[232:235], v[0:3]
	v_mfma_f32_16x16x32_bf16 v[52:55], v[174:177], v[206:209], v[52:55]
	v_mfma_f32_16x16x32_bf16 v[48:51], v[198:201], v[206:209], v[48:51]
	v_mfma_f32_16x16x32_bf16 v[36:39], v[174:177], v[220:223], v[36:39]
	v_mfma_f32_16x16x32_bf16 v[32:35], v[198:201], v[220:223], v[32:35]
	v_mfma_f32_16x16x32_bf16 v[20:23], v[174:177], v[228:231], v[20:23]
	v_mfma_f32_16x16x32_bf16 v[16:19], v[198:201], v[228:231], v[16:19]
	v_mfma_f32_16x16x32_bf16 v[4:7], v[174:177], v[236:239], v[4:7]
	v_mfma_f32_16x16x32_bf16 v[0:3], v[198:201], v[236:239], v[0:3]
	s_barrier
	s_setprio 0
	s_add_u32 s28, s28, 0x100
	s_addc_u32 s29, s29, 0
	s_add_u32 s72, s72, 0x100
	s_addc_u32 s73, s73, 0
	s_cmp_ge_i32 s74, s30
	s_mov_b32 s40, s74
	s_cbranch_scc0 .LBB0_455
	s_and_b64 vcc, exec, s[48:49]
	s_cbranch_vccz .LBB0_458

; #define PG8_STAGE(bufoff, gbase, voff) do { _Pragma("unroll") for (int _i = 0; _i < 2; ++_i) \
;         __builtin_amdgcn_global_load_lds((const unsigned*)((const char*)(gbase) + (voff)[_i]), (LAS unsigned*)(lds + (bufoff) + ldsw + _i * 8192), 16, 0, 0); } while (0)
; #define PG8_LDA(dst, b, h) do { _Pragma("unroll") for (int m = 0; m < 4; ++m) _Pragma("unroll") for (int k = 0; k < 2; ++k) dst[m][k] = *(const LAS bf16x8*)(lds + PG8_SA(b, h) + aoff + m * 2048 + k * 1024); } while (0)
; #define PG8_LDB(dst, b, h) do { _Pragma("unroll") for (int n = 0; n < 2; ++n) _Pragma("unroll") for (int k = 0; k < 2; ++k) dst[n][k] = *(const LAS bf16x8*)(lds + PG8_SB(b, h) + boff + n * 2048 + k * 1024); } while (0)
; #define PG8_MMA(ai, bj, At, Bt) do { __builtin_amdgcn_s_setprio(1); _Pragma("unroll") for (int m = 0; m < 4; ++m) _Pragma("unroll") for (int n = 0; n < 2; ++n) _Pragma("unroll") for (int k = 0; k < 2; ++k) \
;         acc[ai][bj][m][n] = MFMA16(Bt[n][k], At[m][k], acc[ai][bj][m][n]); __builtin_amdgcn_s_setprio(0); } while (0)
; #define PG8_WAIT_V(n) asm volatile("s_waitcnt vmcnt(" #n ")" ::: "memory")
; #define PG8_WAIT_L(n) asm volatile("s_waitcnt lgkmcnt(" #n ")" ::: "memory")
; #define PG8_BAR __builtin_amdgcn_s_barrier()
; #define PG8_SCHED __builtin_amdgcn_sched_barrier(0)
; template <class Epi>
; __device__ __forceinline__ void gemm_phase(LAS unsigned char* lds, const Gemm g, const StaticOrder& S, const Epi& E, int tid_) {
;     ...
;             const bool last = (t == nt - 2);
;             const char* a1 = cA + (size_t)(t + 1) * kstep;
;             const char* a2 = last ? nA : cA + (size_t)(t + 2) * kstep; const char* b2 = last ? nB : cB + (size_t)(t + 2) * kstep;
;             const char* a3 = a2 + kstep; const char* b3 = b2 + kstep;
;             PG8_LDB(B0, 0, 0); PG8_LDB(B1, 0, 1); PG8_SCHED; PG8_LDA(At, 0, 0); PG8_STAGE(PG8_SA(1, 1), a1 + hsA, voffA);
;             PG8_WAIT_V(8); PG8_WAIT_L(0); PG8_BAR; PG8_MMA(0, 0, At, B0); PG8_MMA(0, 1, At, B1); PG8_BAR; PG8_SCHED;
;             PG8_LDA(At, 0, 1); PG8_STAGE(PG8_SB(0, 0), b2, voffB); PG8_STAGE(PG8_SB(0, 1), b2 + hsB, voffB); PG8_STAGE(PG8_SA(0, 0), a2, voffA);
.LBB0_683:
	s_add_i32 s69, s54, 2
	s_add_u32 s70, s28, 0x80
	s_addc_u32 s55, s29, 0
	s_add_i32 s72, 0, 0x10000
	s_cmp_eq_u32 s63, s54
	s_cselect_b32 s55, s41, s55
	s_cselect_b32 s54, s40, s70
	s_cselect_b32 s71, s53, s23
	s_cselect_b32 s70, s52, s22
	s_add_i32 s73, 0, 0x14000
	v_add_u32_e32 v142, s72, v166
	v_add_u32_e32 v169, s73, v166
	ds_read_b128 v[130:133], v142
	ds_read_b128 v[134:137], v142 offset:1024
	ds_read_b128 v[138:141], v142 offset:2048
	ds_read_b128 v[142:145], v142 offset:3072
	ds_read_b128 v[146:149], v169
	ds_read_b128 v[150:153], v169 offset:1024
	ds_read_b128 v[170:173], v169 offset:2048
	ds_read_b128 v[174:177], v169 offset:3072
	v_lshl_add_u64 v[232:233], s[28:29], 0, v[162:163]
	s_add_i32 m0, s56, 0xc000
	ds_read_b128 v[178:181], v168
	ds_read_b128 v[198:201], v168 offset:1024
	ds_read_b128 v[202:205], v168 offset:2048
	ds_read_b128 v[206:209], v168 offset:3072
	ds_read_b128 v[216:219], v168 offset:4096
	ds_read_b128 v[220:223], v168 offset:5120
	ds_read_b128 v[224:227], v168 offset:6144
	ds_read_b128 v[228:231], v168 offset:7168
	global_load_lds_dwordx4 v[232:233], off
	v_lshl_add_u64 v[232:233], s[28:29], 0, v[164:165]
	s_add_i32 m0, s56, 0xe000
	s_nop 0
	global_load_lds_dwordx4 v[232:233], off
	s_waitcnt vmcnt(8)
	s_waitcnt lgkmcnt(0)
	s_setprio 1
	s_barrier
	v_mfma_f32_16x16x32_bf16 v[126:129], v[130:133], v[178:181], v[126:129]
	v_mfma_f32_16x16x32_bf16 v[122:125], v[138:141], v[178:181], v[122:125]
	v_mfma_f32_16x16x32_bf16 v[110:113], v[130:133], v[202:205], v[110:113]
	v_mfma_f32_16x16x32_bf16 v[106:109], v[138:141], v[202:205], v[106:109]
	v_mfma_f32_16x16x32_bf16 v[94:97], v[130:133], v[216:219], v[94:97]
	v_mfma_f32_16x16x32_bf16 v[90:93], v[138:141], v[216:219], v[90:93]
	v_mfma_f32_16x16x32_bf16 v[76:79], v[130:133], v[224:227], v[76:79]
	v_mfma_f32_16x16x32_bf16 v[72:75], v[138:141], v[224:227], v[72:75]
	v_mfma_f32_16x16x32_bf16 v[126:129], v[134:137], v[198:201], v[126:129]
	v_mfma_f32_16x16x32_bf16 v[122:125], v[142:145], v[198:201], v[122:125]
	v_mfma_f32_16x16x32_bf16 v[110:113], v[134:137], v[206:209], v[110:113]
	v_mfma_f32_16x16x32_bf16 v[106:109], v[142:145], v[206:209], v[106:109]
	v_mfma_f32_16x16x32_bf16 v[94:97], v[134:137], v[220:223], v[94:97]
	v_mfma_f32_16x16x32_bf16 v[90:93], v[142:145], v[220:223], v[90:93]
	v_mfma_f32_16x16x32_bf16 v[76:79], v[134:137], v[228:231], v[76:79]
	v_mfma_f32_16x16x32_bf16 v[72:75], v[142:145], v[228:231], v[72:75]
	v_mfma_f32_16x16x32_bf16 v[118:121], v[146:149], v[178:181], v[118:121]
	v_mfma_f32_16x16x32_bf16 v[114:117], v[170:173], v[178:181], v[114:117]
	v_mfma_f32_16x16x32_bf16 v[102:105], v[146:149], v[202:205], v[102:105]
	v_mfma_f32_16x16x32_bf16 v[98:101], v[170:173], v[202:205], v[98:101]
	v_mfma_f32_16x16x32_bf16 v[86:89], v[146:149], v[216:219], v[86:89]
	v_mfma_f32_16x16x32_bf16 v[82:85], v[170:173], v[216:219], v[82:85]
	v_mfma_f32_16x16x32_bf16 v[68:71], v[146:149], v[224:227], v[68:71]
	v_mfma_f32_16x16x32_bf16 v[64:67], v[170:173], v[224:227], v[64:67]
	v_mfma_f32_16x16x32_bf16 v[118:121], v[150:153], v[198:201], v[118:121]
	v_mfma_f32_16x16x32_bf16 v[114:117], v[174:177], v[198:201], v[114:117]
	v_mfma_f32_16x16x32_bf16 v[102:105], v[150:153], v[206:209], v[102:105]
	v_mfma_f32_16x16x32_bf16 v[98:101], v[174:177], v[206:209], v[98:101]
	v_mfma_f32_16x16x32_bf16 v[86:89], v[150:153], v[220:223], v[86:89]
	v_mfma_f32_16x16x32_bf16 v[82:85], v[174:177], v[220:223], v[82:85]
	v_mfma_f32_16x16x32_bf16 v[68:71], v[150:153], v[228:231], v[68:71]
	v_mfma_f32_16x16x32_bf16 v[64:67], v[174:177], v[228:231], v[64:67]
	s_barrier
	s_setprio 0
	s_add_i32 s72, s72, s31
	v_lshl_add_u64 v[232:233], s[70:71], 0, v[156:157]
	s_mov_b32 m0, s72
	ds_read_b128 v[178:181], v168 offset:16384
	ds_read_b128 v[198:201], v168 offset:17408
	ds_read_b128 v[202:205], v168 offset:18432
	ds_read_b128 v[206:209], v168 offset:19456
	ds_read_b128 v[216:219], v168 offset:20480
	ds_read_b128 v[220:223], v168 offset:21504
	ds_read_b128 v[224:227], v168 offset:22528
	ds_read_b128 v[228:231], v168 offset:23552
	global_load_lds_dwordx4 v[232:233], off
	s_add_i32 m0, s72, 0x2000
	v_lshl_add_u64 v[234:235], s[70:71], 0, v[160:161]
	s_add_u32 s70, s70, s4
	s_addc_u32 s71, s71, 0
	s_add_i32 s72, s73, s31
	global_load_lds_dwordx4 v[234:235], off
	v_lshl_add_u64 v[236:237], s[70:71], 0, v[156:157]
	s_mov_b32 m0, s72
	v_lshl_add_u64 v[238:239], s[70:71], 0, v[160:161]
	global_load_lds_dwordx4 v[236:237], off
	s_add_i32 m0, s72, 0x2000
	v_lshl_add_u64 v[240:241], s[54:55], 0, v[154:155]
	global_load_lds_dwordx4 v[238:239], off
	s_mov_b32 m0, s56
	v_lshl_add_u64 v[242:243], s[54:55], 0, v[158:159]
	global_load_lds_dwordx4 v[240:241], off
	s_mov_b32 m0, s57
	s_nop 0
	global_load_lds_dwordx4 v[242:243], off
	s_waitcnt vmcnt(8)
	s_waitcnt lgkmcnt(0)
	s_setprio 1
	s_barrier
; #define PG8_STAGE(bufoff, gbase, voff) do { _Pragma("unroll") for (int _i = 0; _i < 2; ++_i) \
;         __builtin_amdgcn_global_load_lds((const unsigned*)((const char*)(gbase) + (voff)[_i]), (LAS unsigned*)(lds + (bufoff) + ldsw + _i * 8192), 16, 0, 0); } while (0)
; #define PG8_LDA(dst, b, h) do { _Pragma("unroll") for (int m = 0; m < 4; ++m) _Pragma("unroll") for (int k = 0; k < 2; ++k) dst[m][k] = *(const LAS bf16x8*)(lds + PG8_SA(b, h) + aoff + m * 2048 + k * 1024); } while (0)
; #define PG8_LDB(dst, b, h) do { _Pragma("unroll") for (int n = 0; n < 2; ++n) _Pragma("unroll") for (int k = 0; k < 2; ++k) dst[n][k] = *(const LAS bf16x8*)(lds + PG8_SB(b, h) + boff + n * 2048 + k * 1024); } while (0)
; #define PG8_MMA(ai, bj, At, Bt) do { __builtin_amdgcn_s_setprio(1); _Pragma("unroll") for (int m = 0; m < 4; ++m) _Pragma("unroll") for (int n = 0; n < 2; ++n) _Pragma("unroll") for (int k = 0; k < 2; ++k) \
;         acc[ai][bj][m][n] = MFMA16(Bt[n][k], At[m][k], acc[ai][bj][m][n]); __builtin_amdgcn_s_setprio(0); } while (0)
; #define PG8_WAIT_V(n) asm volatile("s_waitcnt vmcnt(" #n ")" ::: "memory")
; #define PG8_WAIT_L(n) asm volatile("s_waitcnt lgkmcnt(" #n ")" ::: "memory")
; #define PG8_BAR __builtin_amdgcn_s_barrier()
; #define PG8_SCHED __builtin_amdgcn_sched_barrier(0)
; template <class Epi>
; __device__ __forceinline__ void gemm_phase(LAS unsigned char* lds, const Gemm g, const StaticOrder& S, const Epi& E, int tid_) {
;     ...
;             PG8_WAIT_V(8); PG8_WAIT_L(0); PG8_BAR; PG8_MMA(1, 0, At, B0); PG8_MMA(1, 1, At, B1); PG8_BAR; PG8_SCHED;
;             PG8_LDB(B0, 1, 0); PG8_LDB(B1, 1, 1); PG8_SCHED; PG8_LDA(At, 1, 0); PG8_STAGE(PG8_SA(0, 1), a2 + hsA, voffA);
;             PG8_WAIT_V(8); PG8_WAIT_L(0); PG8_BAR; PG8_MMA(0, 0, At, B0); PG8_MMA(0, 1, At, B1); PG8_BAR; PG8_SCHED;
	v_mfma_f32_16x16x32_bf16 v[60:63], v[130:133], v[178:181], v[60:63]
	v_mfma_f32_16x16x32_bf16 v[56:59], v[138:141], v[178:181], v[56:59]
	v_mfma_f32_16x16x32_bf16 v[44:47], v[130:133], v[202:205], v[44:47]
	v_mfma_f32_16x16x32_bf16 v[40:43], v[138:141], v[202:205], v[40:43]
	v_mfma_f32_16x16x32_bf16 v[28:31], v[130:133], v[216:219], v[28:31]
	v_mfma_f32_16x16x32_bf16 v[24:27], v[138:141], v[216:219], v[24:27]
	v_mfma_f32_16x16x32_bf16 v[12:15], v[130:133], v[224:227], v[12:15]
	v_mfma_f32_16x16x32_bf16 v[8:11], v[138:141], v[224:227], v[8:11]
	v_mfma_f32_16x16x32_bf16 v[60:63], v[134:137], v[198:201], v[60:63]
	v_mfma_f32_16x16x32_bf16 v[56:59], v[142:145], v[198:201], v[56:59]
	v_mfma_f32_16x16x32_bf16 v[44:47], v[134:137], v[206:209], v[44:47]
	v_mfma_f32_16x16x32_bf16 v[40:43], v[142:145], v[206:209], v[40:43]
	v_mfma_f32_16x16x32_bf16 v[28:31], v[134:137], v[220:223], v[28:31]
	v_mfma_f32_16x16x32_bf16 v[24:27], v[142:145], v[220:223], v[24:27]
	v_mfma_f32_16x16x32_bf16 v[12:15], v[134:137], v[228:231], v[12:15]
	v_mfma_f32_16x16x32_bf16 v[8:11], v[142:145], v[228:231], v[8:11]
	v_mfma_f32_16x16x32_bf16 v[52:55], v[146:149], v[178:181], v[52:55]
	v_mfma_f32_16x16x32_bf16 v[48:51], v[170:173], v[178:181], v[48:51]
	v_mfma_f32_16x16x32_bf16 v[36:39], v[146:149], v[202:205], v[36:39]
	v_mfma_f32_16x16x32_bf16 v[32:35], v[170:173], v[202:205], v[32:35]
	v_mfma_f32_16x16x32_bf16 v[20:23], v[146:149], v[216:219], v[20:23]
	v_mfma_f32_16x16x32_bf16 v[16:19], v[170:173], v[216:219], v[16:19]
	v_mfma_f32_16x16x32_bf16 v[4:7], v[146:149], v[224:227], v[4:7]
	v_mfma_f32_16x16x32_bf16 v[0:3], v[170:173], v[224:227], v[0:3]
	v_mfma_f32_16x16x32_bf16 v[52:55], v[150:153], v[198:201], v[52:55]
	v_mfma_f32_16x16x32_bf16 v[48:51], v[174:177], v[198:201], v[48:51]
	v_mfma_f32_16x16x32_bf16 v[36:39], v[150:153], v[206:209], v[36:39]
	v_mfma_f32_16x16x32_bf16 v[32:35], v[174:177], v[206:209], v[32:35]
	v_mfma_f32_16x16x32_bf16 v[20:23], v[150:153], v[220:223], v[20:23]
	v_mfma_f32_16x16x32_bf16 v[16:19], v[174:177], v[220:223], v[16:19]
	v_mfma_f32_16x16x32_bf16 v[4:7], v[150:153], v[228:231], v[4:7]
	v_mfma_f32_16x16x32_bf16 v[0:3], v[174:177], v[228:231], v[0:3]
	s_barrier
	s_setprio 0
	s_add_i32 s70, 0, 0x18000
	s_add_i32 s71, 0, 0x1c000
	v_add_u32_e32 v142, s70, v166
	v_add_u32_e32 v169, s71, v166
	ds_read_b128 v[130:133], v142
	ds_read_b128 v[134:137], v142 offset:1024
	ds_read_b128 v[138:141], v142 offset:2048
	ds_read_b128 v[142:145], v142 offset:3072
	ds_read_b128 v[146:149], v169
	ds_read_b128 v[150:153], v169 offset:1024
	ds_read_b128 v[170:173], v169 offset:2048
	ds_read_b128 v[174:177], v169 offset:3072
	s_add_u32 s54, s54, s4
	s_addc_u32 s55, s55, 0
	s_mov_b32 m0, s58
	v_lshl_add_u64 v[244:245], s[54:55], 0, v[154:155]
	ds_read_b128 v[178:181], v168 offset:32768
	ds_read_b128 v[198:201], v168 offset:33792
	ds_read_b128 v[202:205], v168 offset:34816
	ds_read_b128 v[206:209], v168 offset:35840
	ds_read_b128 v[216:219], v168 offset:36864
	ds_read_b128 v[220:223], v168 offset:37888
	ds_read_b128 v[224:227], v168 offset:38912
	ds_read_b128 v[228:231], v168 offset:39936
	global_load_lds_dwordx4 v[244:245], off
	v_lshl_add_u64 v[244:245], s[54:55], 0, v[158:159]
	s_mov_b32 m0, s59
	s_nop 0
	global_load_lds_dwordx4 v[244:245], off
	s_waitcnt vmcnt(8)
	s_waitcnt lgkmcnt(0)
	s_setprio 1
	s_barrier
	v_mfma_f32_16x16x32_bf16 v[126:129], v[130:133], v[178:181], v[126:129]
	v_mfma_f32_16x16x32_bf16 v[122:125], v[138:141], v[178:181], v[122:125]
	v_mfma_f32_16x16x32_bf16 v[110:113], v[130:133], v[202:205], v[110:113]
	v_mfma_f32_16x16x32_bf16 v[106:109], v[138:141], v[202:205], v[106:109]
	v_mfma_f32_16x16x32_bf16 v[94:97], v[130:133], v[216:219], v[94:97]
	v_mfma_f32_16x16x32_bf16 v[90:93], v[138:141], v[216:219], v[90:93]
	v_mfma_f32_16x16x32_bf16 v[76:79], v[130:133], v[224:227], v[76:79]
	v_mfma_f32_16x16x32_bf16 v[72:75], v[138:141], v[224:227], v[72:75]
	v_mfma_f32_16x16x32_bf16 v[126:129], v[134:137], v[198:201], v[126:129]
	v_mfma_f32_16x16x32_bf16 v[122:125], v[142:145], v[198:201], v[122:125]
	v_mfma_f32_16x16x32_bf16 v[110:113], v[134:137], v[206:209], v[110:113]
	v_mfma_f32_16x16x32_bf16 v[106:109], v[142:145], v[206:209], v[106:109]
	v_mfma_f32_16x16x32_bf16 v[94:97], v[134:137], v[220:223], v[94:97]
	v_mfma_f32_16x16x32_bf16 v[90:93], v[142:145], v[220:223], v[90:93]
	v_mfma_f32_16x16x32_bf16 v[76:79], v[134:137], v[228:231], v[76:79]
	v_mfma_f32_16x16x32_bf16 v[72:75], v[142:145], v[228:231], v[72:75]
	v_mfma_f32_16x16x32_bf16 v[118:121], v[146:149], v[178:181], v[118:121]
	v_mfma_f32_16x16x32_bf16 v[114:117], v[170:173], v[178:181], v[114:117]
	v_mfma_f32_16x16x32_bf16 v[102:105], v[146:149], v[202:205], v[102:105]
	v_mfma_f32_16x16x32_bf16 v[98:101], v[170:173], v[202:205], v[98:101]
	v_mfma_f32_16x16x32_bf16 v[86:89], v[146:149], v[216:219], v[86:89]
	v_mfma_f32_16x16x32_bf16 v[82:85], v[170:173], v[216:219], v[82:85]
	v_mfma_f32_16x16x32_bf16 v[68:71], v[146:149], v[224:227], v[68:71]
	v_mfma_f32_16x16x32_bf16 v[64:67], v[170:173], v[224:227], v[64:67]
	v_mfma_f32_16x16x32_bf16 v[118:121], v[150:153], v[198:201], v[118:121]
	v_mfma_f32_16x16x32_bf16 v[114:117], v[174:177], v[198:201], v[114:117]
	v_mfma_f32_16x16x32_bf16 v[102:105], v[150:153], v[206:209], v[102:105]
	v_mfma_f32_16x16x32_bf16 v[98:101], v[174:177], v[206:209], v[98:101]
	v_mfma_f32_16x16x32_bf16 v[86:89], v[150:153], v[220:223], v[86:89]
	v_mfma_f32_16x16x32_bf16 v[82:85], v[174:177], v[220:223], v[82:85]
	v_mfma_f32_16x16x32_bf16 v[68:71], v[150:153], v[228:231], v[68:71]
	v_mfma_f32_16x16x32_bf16 v[64:67], v[174:177], v[228:231], v[64:67]
	s_barrier
; #define PG8_STAGE(bufoff, gbase, voff) do { _Pragma("unroll") for (int _i = 0; _i < 2; ++_i) \
;         __builtin_amdgcn_global_load_lds((const unsigned*)((const char*)(gbase) + (voff)[_i]), (LAS unsigned*)(lds + (bufoff) + ldsw + _i * 8192), 16, 0, 0); } while (0)
; #define PG8_LDA(dst, b, h) do { _Pragma("unroll") for (int m = 0; m < 4; ++m) _Pragma("unroll") for (int k = 0; k < 2; ++k) dst[m][k] = *(const LAS bf16x8*)(lds + PG8_SA(b, h) + aoff + m * 2048 + k * 1024); } while (0)
; #define PG8_MMA(ai, bj, At, Bt) do { __builtin_amdgcn_s_setprio(1); _Pragma("unroll") for (int m = 0; m < 4; ++m) _Pragma("unroll") for (int n = 0; n < 2; ++n) _Pragma("unroll") for (int k = 0; k < 2; ++k) \
;         acc[ai][bj][m][n] = MFMA16(Bt[n][k], At[m][k], acc[ai][bj][m][n]); __builtin_amdgcn_s_setprio(0); } while (0)
; #define PG8_WAIT_V(n) asm volatile("s_waitcnt vmcnt(" #n ")" ::: "memory")
; #define PG8_WAIT_L(n) asm volatile("s_waitcnt lgkmcnt(" #n ")" ::: "memory")
; #define PG8_BAR __builtin_amdgcn_s_barrier()
; #define PG8_SCHED __builtin_amdgcn_sched_barrier(0)
; template <class Epi>
; __device__ __forceinline__ void gemm_phase(LAS unsigned char* lds, const Gemm g, const StaticOrder& S, const Epi& E, int tid_) {
;     ...
;             PG8_LDA(At, 1, 1); PG8_STAGE(PG8_SB(1, 0), b3, voffB); PG8_STAGE(PG8_SB(1, 1), b3 + hsB, voffB); PG8_STAGE(PG8_SA(1, 0), a3, voffA);
;             PG8_WAIT_V(8); PG8_WAIT_L(0); PG8_BAR; PG8_MMA(1, 0, At, B0); PG8_MMA(1, 1, At, B1); PG8_BAR; PG8_SCHED;
;         }
	s_setprio 0
	s_add_i32 s54, s70, s31
	v_lshl_add_u64 v[232:233], v[232:233], 0, s[6:7]
	s_mov_b32 m0, s54
	ds_read_b128 v[178:181], v168 offset:49152
	ds_read_b128 v[198:201], v168 offset:50176
	ds_read_b128 v[202:205], v168 offset:51200
	ds_read_b128 v[206:209], v168 offset:52224
	ds_read_b128 v[216:219], v168 offset:53248
	ds_read_b128 v[220:223], v168 offset:54272
	ds_read_b128 v[224:227], v168 offset:55296
	ds_read_b128 v[228:231], v168 offset:56320
	global_load_lds_dwordx4 v[232:233], off
	v_lshl_add_u64 v[232:233], v[234:235], 0, s[6:7]
	s_add_i32 m0, s54, 0x2000
	s_add_i32 s54, s71, s31
	global_load_lds_dwordx4 v[232:233], off
	v_lshl_add_u64 v[232:233], v[236:237], 0, s[6:7]
	s_mov_b32 m0, s54
	s_nop 0
	global_load_lds_dwordx4 v[232:233], off
	v_lshl_add_u64 v[232:233], v[238:239], 0, s[6:7]
	s_add_i32 m0, s54, 0x2000
	s_nop 0
	global_load_lds_dwordx4 v[232:233], off
	v_lshl_add_u64 v[232:233], v[240:241], 0, s[6:7]
	s_mov_b32 m0, s60
	s_nop 0
	global_load_lds_dwordx4 v[232:233], off
	v_lshl_add_u64 v[232:233], v[242:243], 0, s[6:7]
	s_mov_b32 m0, s61
	s_nop 0
	global_load_lds_dwordx4 v[232:233], off
	s_waitcnt vmcnt(8)
	s_waitcnt lgkmcnt(0)
	s_setprio 1
	s_barrier
	v_mfma_f32_16x16x32_bf16 v[60:63], v[130:133], v[178:181], v[60:63]
	v_mfma_f32_16x16x32_bf16 v[56:59], v[138:141], v[178:181], v[56:59]
	v_mfma_f32_16x16x32_bf16 v[44:47], v[130:133], v[202:205], v[44:47]
	v_mfma_f32_16x16x32_bf16 v[40:43], v[138:141], v[202:205], v[40:43]
	v_mfma_f32_16x16x32_bf16 v[28:31], v[130:133], v[216:219], v[28:31]
	v_mfma_f32_16x16x32_bf16 v[24:27], v[138:141], v[216:219], v[24:27]
	v_mfma_f32_16x16x32_bf16 v[12:15], v[130:133], v[224:227], v[12:15]
	v_mfma_f32_16x16x32_bf16 v[8:11], v[138:141], v[224:227], v[8:11]
	v_mfma_f32_16x16x32_bf16 v[60:63], v[134:137], v[198:201], v[60:63]
	v_mfma_f32_16x16x32_bf16 v[56:59], v[142:145], v[198:201], v[56:59]
	v_mfma_f32_16x16x32_bf16 v[44:47], v[134:137], v[206:209], v[44:47]
	v_mfma_f32_16x16x32_bf16 v[40:43], v[142:145], v[206:209], v[40:43]
	v_mfma_f32_16x16x32_bf16 v[28:31], v[134:137], v[220:223], v[28:31]
	v_mfma_f32_16x16x32_bf16 v[24:27], v[142:145], v[220:223], v[24:27]
	v_mfma_f32_16x16x32_bf16 v[12:15], v[134:137], v[228:231], v[12:15]
	v_mfma_f32_16x16x32_bf16 v[8:11], v[142:145], v[228:231], v[8:11]
	v_mfma_f32_16x16x32_bf16 v[52:55], v[146:149], v[178:181], v[52:55]
	v_mfma_f32_16x16x32_bf16 v[48:51], v[170:173], v[178:181], v[48:51]
	v_mfma_f32_16x16x32_bf16 v[36:39], v[146:149], v[202:205], v[36:39]
	v_mfma_f32_16x16x32_bf16 v[32:35], v[170:173], v[202:205], v[32:35]
	v_mfma_f32_16x16x32_bf16 v[20:23], v[146:149], v[216:219], v[20:23]
	v_mfma_f32_16x16x32_bf16 v[16:19], v[170:173], v[216:219], v[16:19]
	v_mfma_f32_16x16x32_bf16 v[4:7], v[146:149], v[224:227], v[4:7]
	v_mfma_f32_16x16x32_bf16 v[0:3], v[170:173], v[224:227], v[0:3]
	v_mfma_f32_16x16x32_bf16 v[52:55], v[150:153], v[198:201], v[52:55]
	v_mfma_f32_16x16x32_bf16 v[48:51], v[174:177], v[198:201], v[48:51]
	v_mfma_f32_16x16x32_bf16 v[36:39], v[150:153], v[206:209], v[36:39]
	v_mfma_f32_16x16x32_bf16 v[32:35], v[174:177], v[206:209], v[32:35]
	v_mfma_f32_16x16x32_bf16 v[20:23], v[150:153], v[220:223], v[20:23]
	v_mfma_f32_16x16x32_bf16 v[16:19], v[174:177], v[220:223], v[16:19]
	v_mfma_f32_16x16x32_bf16 v[4:7], v[150:153], v[228:231], v[4:7]
	v_mfma_f32_16x16x32_bf16 v[0:3], v[174:177], v[228:231], v[0:3]
	s_barrier
	s_setprio 0
	s_add_u32 s28, s28, 0x100
	s_addc_u32 s29, s29, 0
	s_add_u32 s22, s22, 0x100
	s_addc_u32 s23, s23, 0
	s_cmp_ge_i32 s69, s1
	s_mov_b32 s54, s69
	s_cbranch_scc0 .LBB0_683
	s_and_b64 vcc, exec, s[50:51]
	s_cbranch_vccz .LBB0_686
